# v45 + ff2 processes its two m-tile groups in reverse order (most recently written half of the FFN hidden first, for memory-side cache reuse)
# speedup vs baseline: 1.0108x; 1.0108x over previous
; DI int TID8() { int t = threadIdx.x; asm volatile("" : "+v"(t)); return t; }
; DI void gemm8_accum(f32x4 (&acc)[8][4], const bf16_t* a, size_t lda, const bf16_t* b, size_t ldb, int nkb, bf16_t* L,
;                     const bool pre, const bf16_t* an, size_t ldan, const bf16_t* bn, size_t ldbn) {
;   const int tid = TID8(), lane = tid & 63, w = tid >> 6;
;   const int wm = w >> 2, wn = w & 3;
;   const int lrow = tid >> 3, lch = tid & 7;
;   u32x4 ra[4], rb[4];
;   unsigned offa[4], offb[4];
; #pragma unroll
;   for (int i = 0; i < 4; ++i) {
;     offa[i] = (unsigned)(lrow + 64 * i) * (unsigned)lda + (unsigned)(lch * 8);
;     offb[i] = (unsigned)(lrow + 64 * i) * (unsigned)ldb + (unsigned)(lch * 8);
;   }
;   if (!pre) {
;     g8_load1o(ra, a, offa);
;     g8_load1o(rb, b, offb);
;     __syncthreads();
;     g8_store(L, ra, rb, lrow, lch);
;   }
; __global__ void __launch_bounds__(512, 2) mega(Params p) {
;     ...
;     GEMM8_TILE_LOOP(4) {
;       const int m0 = mt * 256, n0 = ntile * 256;
;       f32x4 acc8[8][4];
;       zero_acc8(acc8);
;       gemm8_accum(acc8, ubuf + (size_t)m0 * 4096, 4096, wl + W_FF2 + (size_t)n0 * 4096, 4096, 64, lds_all, !first_,
;                   ubuf + (size_t)mtn * 256 * 4096, 4096, wl + W_FF2 + (size_t)ntilen * 256 * 4096, 4096);
.LBB0_937:
	s_lshl_b32 s0, s13, 1
	s_and_b32 s0, s0, 0x60
	s_and_b32 s1, s13, 3
	s_or_b32 s0, s1, s0
	v_readlane_b32 s1, v252, 25
	s_or_b32 s12, s0, s1
	s_xor_b32 s12, s12, 0x40
	s_bfe_u32 s11, s13, 0x20002
	s_lshl_b32 s0, s12, 21
	v_mov_b32_e32 v36, v196
	s_add_u32 s2, s16, s0
	s_addc_u32 s3, s17, 0
	v_ashrrev_i32_e32 v8, 3, v36
	v_lshlrev_b32_e32 v0, 3, v36
	s_lshl_b32 s0, s11, 21
	v_readlane_b32 s20, v251, 59
	v_and_b32_e32 v34, 56, v0
	v_lshlrev_b32_e32 v35, 12, v8
	v_readlane_b32 s21, v251, 60
	s_add_u32 s0, s20, s0
	v_or_b32_e32 v2, v35, v34
	v_mov_b32_e32 v3, v1
	s_addc_u32 s1, s21, 0
	v_lshlrev_b64 v[164:165], 1, v[2:3]
	v_lshrrev_b32_e32 v7, 1, v8
	v_add_u32_e32 v168, 0x40000, v2
	v_add_u32_e32 v166, 0x80000, v2
	v_add_u32_e32 v0, 0xc0000, v2
	v_mov_b32_e32 v167, v1
	v_mov_b32_e32 v169, v1
	s_andn2_b64 vcc, exec, s[6:7]
	v_lshl_add_u64 v[4:5], s[2:3], 0, v[164:165]
	v_lshl_add_u64 v[2:3], s[0:1], 0, v[164:165]
	v_lshlrev_b32_e32 v6, 6, v8
	v_xor_b32_e32 v7, v7, v36
	s_cbranch_vccz .LBB0_939
	v_lshlrev_b64 v[26:27], 1, v[168:169]
	v_lshlrev_b64 v[38:39], 1, v[166:167]
	v_lshlrev_b64 v[44:45], 1, v[0:1]
	v_lshl_add_u64 v[10:11], s[2:3], 0, v[26:27]
	v_lshl_add_u64 v[14:15], s[2:3], 0, v[38:39]
	v_lshl_add_u64 v[28:29], s[2:3], 0, v[44:45]
	v_lshl_add_u64 v[30:31], s[0:1], 0, v[26:27]
	global_load_dwordx4 v[10:13], v[10:11], off
	s_nop 0
	global_load_dwordx4 v[14:17], v[14:15], off
	s_nop 0
	global_load_dwordx4 v[18:21], v[4:5], off
	global_load_dwordx4 v[22:25], v[2:3], off
	s_nop 0
	global_load_dwordx4 v[26:29], v[28:29], off
	s_nop 0
	global_load_dwordx4 v[30:33], v[30:31], off
	v_lshl_add_u64 v[38:39], s[0:1], 0, v[38:39]
	global_load_dwordx4 v[40:43], v[38:39], off
	v_lshl_add_u64 v[38:39], s[0:1], 0, v[44:45]
	global_load_dwordx4 v[44:47], v[38:39], off
	v_lshlrev_b32_e32 v37, 6, v8
	v_lshlrev_b32_e32 v8, 3, v7
	v_and_b32_e32 v38, 56, v8
	v_or_b32_e32 v8, v38, v37
	v_lshl_add_u32 v8, v8, 1, 0
	s_barrier
	s_waitcnt vmcnt(5)
	ds_write_b128 v8, v[18:21]
	s_waitcnt vmcnt(4)
	ds_write_b128 v8, v[22:25] offset:32768
	ds_write_b128 v8, v[10:13] offset:8192
	s_waitcnt vmcnt(2)
	ds_write_b128 v8, v[30:33] offset:40960
	ds_write_b128 v8, v[14:17] offset:16384
	s_waitcnt vmcnt(1)
	ds_write_b128 v8, v[40:43] offset:49152
	ds_write_b128 v8, v[26:29] offset:24576
	s_waitcnt vmcnt(0)
	ds_write_b128 v8, v[44:47] offset:57344
	s_cbranch_execz .LBB0_940
	s_branch .LBB0_941

; DI int TID8() { int t = threadIdx.x; asm volatile("" : "+v"(t)); return t; }
; DI void gemm8_accum(f32x4 (&acc)[8][4], const bf16_t* a, size_t lda, const bf16_t* b, size_t ldb, int nkb, bf16_t* L,
;                     const bool pre, const bf16_t* an, size_t ldan, const bf16_t* bn, size_t ldbn) {
;   const int tid = TID8(), lane = tid & 63, w = tid >> 6;
;   const int wm = w >> 2, wn = w & 3;
;   const int lrow = tid >> 3, lch = tid & 7;
;   u32x4 ra[4], rb[4];
;   unsigned offa[4], offb[4];
; #pragma unroll
;   for (int i = 0; i < 4; ++i) {
;     offa[i] = (unsigned)(lrow + 64 * i) * (unsigned)lda + (unsigned)(lch * 8);
;     offb[i] = (unsigned)(lrow + 64 * i) * (unsigned)ldb + (unsigned)(lch * 8);
;   }
;   if (!pre) {
;     g8_load1o(ra, a, offa);
;     g8_load1o(rb, b, offb);
;     __syncthreads();
;     g8_store(L, ra, rb, lrow, lch);
;   }
;   g8_load1o(ra, a + 64, offa);
;   g8_load1o(rb, b + 64, offb);
.LBB0_941:
	v_lshlrev_b64 v[40:41], 1, v[168:169]
	v_lshl_add_u64 v[6:7], s[2:3], 0, v[40:41]
	v_lshlrev_b64 v[42:43], 1, v[166:167]
	v_lshlrev_b64 v[44:45], 1, v[0:1]
	v_lshl_add_u64 v[8:9], s[2:3], 0, v[42:43]
	global_load_dwordx4 v[18:21], v[6:7], off offset:128
	global_load_dwordx4 v[26:29], v[8:9], off offset:128
	v_lshl_add_u64 v[6:7], s[2:3], 0, v[44:45]
	global_load_dwordx4 v[22:25], v[4:5], off offset:128
	global_load_dwordx4 v[30:33], v[6:7], off offset:128
	global_load_dwordx4 v[14:17], v[2:3], off offset:128
	v_lshl_add_u64 v[2:3], s[0:1], 0, v[40:41]
	s_nop 1
	global_load_dwordx4 v[2:5], v[2:3], off offset:128
	v_lshl_add_u64 v[6:7], s[0:1], 0, v[42:43]
	v_lshl_add_u64 v[10:11], s[0:1], 0, v[44:45]
	global_load_dwordx4 v[6:9], v[6:7], off offset:128
	s_nop 0
	global_load_dwordx4 v[10:13], v[10:11], off offset:128
	v_bfe_u32 v39, v36, 4, 2
	v_lshrrev_b32_e32 v46, 1, v36
	s_lshl_b32 s6, s12, 8
	s_and_b32 s12, s10, 0x60
	v_readlane_b32 s20, v252, 25
	v_bitop3_b32 v46, v46, v39, 7 bitop3:0x6c
	s_lshr_b32 s7, s13, 2
	s_or_b32 s12, s20, s12
	s_and_b32 s20, s9, 3
	v_lshlrev_b32_e32 v191, 3, v46
	v_lshlrev_b32_e32 v46, 5, v36
	s_and_b32 s7, s7, 3
	s_add_i32 s12, s12, s20
	s_xor_b32 s12, s12, 0x40
	v_bfe_u32 v47, v36, 1, 3
	v_and_b32_e32 v46, 0xffffe000, v46
	v_lshlrev_b32_e32 v36, 6, v36
	s_movk_i32 s0, 0x3c0
	s_lshl_b32 s7, s7, 21
	s_lshl_b32 s12, s12, 21
	v_and_or_b32 v46, v36, s0, v46
	v_readlane_b32 s0, v254, 30
	s_add_u32 s0, s0, s7
	v_readlane_b32 s1, v254, 31
	v_add_u32_e32 v34, v35, v34
	v_mov_b32_e32 v35, v1
	s_addc_u32 s1, s1, 0
	v_lshlrev_b64 v[34:35], 1, v[34:35]
	v_lshl_add_u64 v[170:171], s[0:1], 0, v[44:45]
	v_lshl_add_u64 v[172:173], s[0:1], 0, v[42:43]
	v_lshl_add_u64 v[174:175], s[0:1], 0, v[40:41]
	v_lshl_add_u64 v[176:177], s[0:1], 0, v[34:35]
	v_readlane_b32 s0, v254, 32
	s_add_u32 s0, s0, s12
	v_readlane_b32 s1, v254, 33
	s_addc_u32 s1, s1, 0
	v_and_b32_e32 v36, 0x33c0, v36
	v_bitop3_b32 v39, v39, v47, 4 bitop3:0x36
	v_lshlrev_b32_e32 v189, 1, v38
	v_lshlrev_b32_e32 v190, 1, v37
	v_lshl_add_u64 v[184:185], s[0:1], 0, v[34:35]
	v_mov_b32_e32 v34, 0
	v_lshlrev_b32_e32 v188, 3, v39
	v_add3_u32 v163, 0, v189, v190
	v_lshl_add_u64 v[178:179], s[0:1], 0, v[44:45]
	v_lshl_add_u64 v[180:181], s[0:1], 0, v[42:43]
	v_lshl_add_u64 v[182:183], s[0:1], 0, v[40:41]
	s_mov_b64 s[0:1], 0
	s_mov_b32 s2, 0
	v_lshlrev_b32_e32 v187, 1, v46
	v_lshlrev_b32_e32 v186, 1, v36
	v_mov_b32_e32 v35, v34
	v_mov_b64_e32 v[36:37], v[34:35]
	v_mov_b64_e32 v[38:39], v[34:35]
	v_mov_b64_e32 v[40:41], v[34:35]
	v_mov_b64_e32 v[42:43], v[34:35]
	v_mov_b64_e32 v[44:45], v[34:35]
	v_mov_b64_e32 v[46:47], v[34:35]
	v_mov_b64_e32 v[48:49], v[34:35]
	v_mov_b64_e32 v[50:51], v[34:35]
	v_mov_b64_e32 v[52:53], v[34:35]
	v_mov_b64_e32 v[54:55], v[34:35]
	v_mov_b64_e32 v[56:57], v[34:35]
	v_mov_b64_e32 v[58:59], v[34:35]
	v_mov_b64_e32 v[60:61], v[34:35]
	v_mov_b64_e32 v[62:63], v[34:35]
	v_mov_b64_e32 v[64:65], v[34:35]
	v_mov_b64_e32 v[66:67], v[34:35]
	v_mov_b64_e32 v[68:69], v[34:35]
	v_mov_b64_e32 v[70:71], v[34:35]
	v_mov_b64_e32 v[72:73], v[34:35]
	v_mov_b64_e32 v[74:75], v[34:35]
	v_mov_b64_e32 v[76:77], v[34:35]
	v_mov_b64_e32 v[78:79], v[34:35]
	v_mov_b64_e32 v[80:81], v[34:35]
	v_mov_b64_e32 v[82:83], v[34:35]
	v_mov_b64_e32 v[84:85], v[34:35]
	v_mov_b64_e32 v[86:87], v[34:35]
	v_mov_b64_e32 v[88:89], v[34:35]
	v_mov_b64_e32 v[90:91], v[34:35]
	v_mov_b64_e32 v[92:93], v[34:35]
	v_mov_b64_e32 v[94:95], v[34:35]
	v_mov_b64_e32 v[96:97], v[34:35]
	v_mov_b64_e32 v[98:99], v[34:35]
	v_mov_b64_e32 v[100:101], v[34:35]
	v_mov_b64_e32 v[102:103], v[34:35]
	v_mov_b64_e32 v[104:105], v[34:35]
	v_mov_b64_e32 v[106:107], v[34:35]
	v_mov_b64_e32 v[108:109], v[34:35]
	v_mov_b64_e32 v[110:111], v[34:35]
	v_mov_b64_e32 v[112:113], v[34:35]
	v_mov_b64_e32 v[114:115], v[34:35]
	v_mov_b64_e32 v[116:117], v[34:35]
	v_mov_b64_e32 v[118:119], v[34:35]
	v_mov_b64_e32 v[120:121], v[34:35]
	v_mov_b64_e32 v[122:123], v[34:35]
	v_mov_b64_e32 v[124:125], v[34:35]
	v_mov_b64_e32 v[126:127], v[34:35]
	v_mov_b64_e32 v[128:129], v[34:35]
	v_mov_b64_e32 v[130:131], v[34:35]
	v_mov_b64_e32 v[132:133], v[34:35]
	v_mov_b64_e32 v[134:135], v[34:35]
	v_mov_b64_e32 v[136:137], v[34:35]
	v_mov_b64_e32 v[138:139], v[34:35]
	v_mov_b64_e32 v[140:141], v[34:35]
	v_mov_b64_e32 v[142:143], v[34:35]
	v_mov_b64_e32 v[144:145], v[34:35]
	v_mov_b64_e32 v[146:147], v[34:35]
	v_mov_b64_e32 v[148:149], v[34:35]
	v_mov_b64_e32 v[150:151], v[34:35]
	v_mov_b64_e32 v[152:153], v[34:35]
	v_mov_b64_e32 v[154:155], v[34:35]
	v_mov_b64_e32 v[156:157], v[34:35]
	v_mov_b64_e32 v[158:159], v[34:35]
	v_mov_b64_e32 v[160:161], v[34:35]
	v_readfirstlane_b32 s52, v184
	v_readfirstlane_b32 s53, v185
	s_sub_u32 s52, s52, 0x40000000
	s_subb_u32 s53, s53, 0
	v_readfirstlane_b32 s56, v176
	v_readfirstlane_b32 s57, v177
	s_sub_u32 s56, s56, 0x40000000
	s_subb_u32 s57, s57, 0
	v_subrev_u32_e32 v185, s52, v184
	v_subrev_u32_e32 v181, s52, v180
	v_subrev_u32_e32 v179, s52, v178
	v_subrev_u32_e32 v183, s52, v182
	v_subrev_u32_e32 v177, s56, v176
	v_subrev_u32_e32 v175, s56, v174
	v_subrev_u32_e32 v173, s56, v172
	v_subrev_u32_e32 v171, s56, v170
	v_lshl_add_u32 v170, v191, 1, v187
	v_lshl_add_u32 v172, v191, 1, v186
	v_lshl_add_u32 v174, v188, 1, v187
	v_lshl_add_u32 v176, v188, 1, v186

; DI void gemm8_accum(f32x4 (&acc)[8][4], const bf16_t* a, size_t lda, const bf16_t* b, size_t ldb, int nkb, bf16_t* L,
;                     const bool pre, const bf16_t* an, size_t ldan, const bf16_t* bn, size_t ldbn) {
;     ...
;   __syncthreads();
;   g8_store1(L + 32768, ra, lrow, lch);
;   g8_load1(ra, an, ldan, 0, lrow, lch);
;   __builtin_amdgcn_sched_barrier(0);
;   g8_compute<0, 1>(acc, L, wm, wn, lane);
;   __builtin_amdgcn_sched_barrier(0);
;   g8_store1(L + 32768 + 16384, rb, lrow, lch);
;   g8_load1(rb, bn, ldbn, 0, lrow, lch);
;   __builtin_amdgcn_sched_barrier(0);
;   g8_compute<1, 2>(acc, L, wm, wn, lane);
;   __syncthreads();
;   g8_store1(L, ra, lrow, lch);
;   __builtin_amdgcn_sched_barrier(0);
;   g8_compute<0, 1>(acc, L + 32768, wm, wn, lane);
.Lstg_942_c:
	v_readlane_b32 s0, v254, 18
	s_add_i32 s12, s13, s0
	s_cmp_gt_u32 s12, 63
	s_cselect_b64 s[0:1], -1, 0
	s_cmp_lt_u32 s12, 64
	s_cselect_b32 s7, s12, s13
	s_lshl_b32 s2, s7, 1
	s_and_b32 s2, s2, 0x7fffffe0
	s_and_b32 s3, s7, 3
	s_or_b32 s2, s3, s2
	v_readlane_b32 s3, v252, 25
	s_or_b32 s28, s2, s3
	s_xor_b32 s28, s28, 0x40
	s_lshl_b32 s13, s11, 8
	s_lshl_b64 s[2:3], s[28:29], 21
	s_add_u32 s2, s16, s2
	v_mov_b32_e32 v169, v1
	v_mov_b32_e32 v167, v1
	s_addc_u32 s3, s17, s3
	v_lshlrev_b64 v[184:185], 1, v[168:169]
	v_lshlrev_b64 v[166:167], 1, v[166:167]
	v_lshlrev_b64 v[226:227], 1, v[0:1]
	v_lshl_add_u64 v[170:171], s[2:3], 0, v[164:165]
	v_lshl_add_u64 v[172:173], s[2:3], 0, v[184:185]
	v_lshl_add_u64 v[176:177], s[2:3], 0, v[166:167]
	v_lshl_add_u64 v[180:181], s[2:3], 0, v[226:227]
	s_barrier
	global_load_dwordx4 v[168:171], v[170:171], off
	s_nop 0
	global_load_dwordx4 v[172:175], v[172:173], off
	s_nop 0
	global_load_dwordx4 v[176:179], v[176:177], off
	s_nop 0
	global_load_dwordx4 v[180:183], v[180:181], off
	s_lshl_b32 s2, s7, 19
	s_and_b32 s2, s2, 0x600000
	v_readlane_b32 s20, v251, 59
	v_readlane_b32 s21, v251, 60
	s_add_u32 s2, s20, s2
	s_addc_u32 s3, s21, 0
	s_add_i32 s7, 0, 0x10000
	v_add3_u32 v0, s7, v189, v190
	s_waitcnt vmcnt(11)
	ds_write_b128 v0, v[22:25]
	s_waitcnt vmcnt(9)
	ds_write_b128 v0, v[18:21] offset:8192
	ds_write_b128 v0, v[26:29] offset:16384
	s_waitcnt vmcnt(8)
	ds_write_b128 v0, v[30:33] offset:24576
	v_lshlrev_b32_e32 v0, 1, v191
	v_add_u32_e32 v191, 0, v0
	v_add_u32_e32 v206, v191, v187
	ds_read_b128 v[18:21], v206
	ds_read_b128 v[22:25], v206 offset:2048
	ds_read_b128 v[26:29], v206 offset:4096
	ds_read_b128 v[30:33], v206 offset:6144
	ds_read_b128 v[192:195], v206 offset:8192
	ds_read_b128 v[198:201], v206 offset:10240
	ds_read_b128 v[202:205], v206 offset:12288
	ds_read_b128 v[206:209], v206 offset:14336
	v_add_u32_e32 v191, v191, v186
	ds_read_b128 v[210:213], v191 offset:32768
	ds_read_b128 v[214:217], v191 offset:34816
	ds_read_b128 v[218:221], v191 offset:36864
	ds_read_b128 v[222:225], v191 offset:38912
	s_waitcnt lgkmcnt(3)
	v_mfma_f32_16x16x32_bf16 v[158:161], v[210:213], v[18:21], v[158:161]
	s_waitcnt lgkmcnt(2)
	v_mfma_f32_16x16x32_bf16 v[154:157], v[214:217], v[18:21], v[154:157]
	s_waitcnt lgkmcnt(1)
	v_mfma_f32_16x16x32_bf16 v[150:153], v[218:221], v[18:21], v[150:153]
	s_waitcnt lgkmcnt(0)
	v_mfma_f32_16x16x32_bf16 v[18:21], v[222:225], v[18:21], v[146:149]
	v_mfma_f32_16x16x32_bf16 v[142:145], v[210:213], v[22:25], v[142:145]
	v_mfma_f32_16x16x32_bf16 v[138:141], v[214:217], v[22:25], v[138:141]
	v_mfma_f32_16x16x32_bf16 v[134:137], v[218:221], v[22:25], v[134:137]
	v_mfma_f32_16x16x32_bf16 v[22:25], v[222:225], v[22:25], v[130:133]
	v_mfma_f32_16x16x32_bf16 v[126:129], v[210:213], v[26:29], v[126:129]
	v_mfma_f32_16x16x32_bf16 v[122:125], v[214:217], v[26:29], v[122:125]
	v_mfma_f32_16x16x32_bf16 v[118:121], v[218:221], v[26:29], v[118:121]
	v_mfma_f32_16x16x32_bf16 v[26:29], v[222:225], v[26:29], v[114:117]
	v_mfma_f32_16x16x32_bf16 v[110:113], v[210:213], v[30:33], v[110:113]
	v_mfma_f32_16x16x32_bf16 v[106:109], v[214:217], v[30:33], v[106:109]
	v_mfma_f32_16x16x32_bf16 v[102:105], v[218:221], v[30:33], v[102:105]
	v_mfma_f32_16x16x32_bf16 v[30:33], v[222:225], v[30:33], v[98:101]
	v_mfma_f32_16x16x32_bf16 v[94:97], v[210:213], v[192:195], v[94:97]
	v_mfma_f32_16x16x32_bf16 v[90:93], v[214:217], v[192:195], v[90:93]
	v_mfma_f32_16x16x32_bf16 v[86:89], v[218:221], v[192:195], v[86:89]
	v_mfma_f32_16x16x32_bf16 v[82:85], v[222:225], v[192:195], v[82:85]
	v_mfma_f32_16x16x32_bf16 v[78:81], v[210:213], v[198:201], v[78:81]
	v_mfma_f32_16x16x32_bf16 v[74:77], v[214:217], v[198:201], v[74:77]
	v_mfma_f32_16x16x32_bf16 v[70:73], v[218:221], v[198:201], v[70:73]
	v_mfma_f32_16x16x32_bf16 v[66:69], v[222:225], v[198:201], v[66:69]
	v_mfma_f32_16x16x32_bf16 v[62:65], v[210:213], v[202:205], v[62:65]
	v_mfma_f32_16x16x32_bf16 v[58:61], v[214:217], v[202:205], v[58:61]
	v_mfma_f32_16x16x32_bf16 v[54:57], v[218:221], v[202:205], v[54:57]
	v_mfma_f32_16x16x32_bf16 v[50:53], v[222:225], v[202:205], v[50:53]
	v_mfma_f32_16x16x32_bf16 v[46:49], v[210:213], v[206:209], v[46:49]
	v_mfma_f32_16x16x32_bf16 v[42:45], v[214:217], v[206:209], v[42:45]
	v_mfma_f32_16x16x32_bf16 v[38:41], v[218:221], v[206:209], v[38:41]
	v_mfma_f32_16x16x32_bf16 v[34:37], v[222:225], v[206:209], v[34:37]
	v_readlane_b32 s20, v254, 36
	s_nop 1
	v_add3_u32 v98, s20, v189, v190
	s_waitcnt vmcnt(7)
	ds_write_b128 v98, v[14:17]
	s_waitcnt vmcnt(6)
	ds_write_b128 v98, v[2:5] offset:8192
	s_waitcnt vmcnt(5)
	ds_write_b128 v98, v[6:9] offset:16384
	s_waitcnt vmcnt(4)
	ds_write_b128 v98, v[10:13] offset:24576
	v_lshl_add_u64 v[2:3], s[2:3], 0, v[164:165]
	v_lshl_add_u64 v[6:7], s[2:3], 0, v[184:185]
	v_lshl_add_u64 v[10:11], s[2:3], 0, v[166:167]
	v_lshl_add_u64 v[14:15], s[2:3], 0, v[226:227]
	global_load_dwordx4 v[2:5], v[2:3], off
	s_nop 0
	global_load_dwordx4 v[6:9], v[6:7], off
	s_nop 0
	global_load_dwordx4 v[10:13], v[10:11], off
	s_nop 0
	global_load_dwordx4 v[14:17], v[14:15], off
	v_lshlrev_b32_e32 v184, 1, v188
	v_add_u32_e32 v185, 0, v184
	v_add_u32_e32 v198, v185, v187
	ds_read_b128 v[98:101], v198
	ds_read_b128 v[114:117], v198 offset:2048
	ds_read_b128 v[130:133], v198 offset:4096
	ds_read_b128 v[146:149], v198 offset:6144
	ds_read_b128 v[164:167], v198 offset:8192
	ds_read_b128 v[188:191], v198 offset:10240
	ds_read_b128 v[192:195], v198 offset:12288
	ds_read_b128 v[198:201], v198 offset:14336
	v_add_u32_e32 v185, v185, v186
	ds_read_b128 v[202:205], v185 offset:32768
	ds_read_b128 v[206:209], v185 offset:34816
	ds_read_b128 v[210:213], v185 offset:36864
	ds_read_b128 v[214:217], v185 offset:38912
	s_waitcnt lgkmcnt(3)
; DI void gemm8_accum(f32x4 (&acc)[8][4], const bf16_t* a, size_t lda, const bf16_t* b, size_t ldb, int nkb, bf16_t* L,
;                     const bool pre, const bf16_t* an, size_t ldan, const bf16_t* bn, size_t ldbn) {
;     ...
;   g8_compute<1, 2>(acc, L, wm, wn, lane);
;   __syncthreads();
;   g8_store1(L, ra, lrow, lch);
;   __builtin_amdgcn_sched_barrier(0);
;   g8_compute<0, 1>(acc, L + 32768, wm, wn, lane);
;   __builtin_amdgcn_sched_barrier(0);
;   g8_store1(L + 16384, rb, lrow, lch);
;   __builtin_amdgcn_sched_barrier(0);
;   g8_compute<1, 2>(acc, L + 32768, wm, wn, lane);
	v_mfma_f32_16x16x32_bf16 v[158:161], v[202:205], v[98:101], v[158:161]
	s_waitcnt lgkmcnt(2)
	v_mfma_f32_16x16x32_bf16 v[154:157], v[206:209], v[98:101], v[154:157]
	s_waitcnt lgkmcnt(1)
	v_mfma_f32_16x16x32_bf16 v[150:153], v[210:213], v[98:101], v[150:153]
	s_waitcnt lgkmcnt(0)
	v_mfma_f32_16x16x32_bf16 v[18:21], v[214:217], v[98:101], v[18:21]
	v_mfma_f32_16x16x32_bf16 v[98:101], v[202:205], v[114:117], v[142:145]
	v_mfma_f32_16x16x32_bf16 v[138:141], v[206:209], v[114:117], v[138:141]
	v_mfma_f32_16x16x32_bf16 v[134:137], v[210:213], v[114:117], v[134:137]
	v_mfma_f32_16x16x32_bf16 v[22:25], v[214:217], v[114:117], v[22:25]
	v_mfma_f32_16x16x32_bf16 v[114:117], v[202:205], v[130:133], v[126:129]
	v_mfma_f32_16x16x32_bf16 v[122:125], v[206:209], v[130:133], v[122:125]
	v_mfma_f32_16x16x32_bf16 v[118:121], v[210:213], v[130:133], v[118:121]
	v_mfma_f32_16x16x32_bf16 v[26:29], v[214:217], v[130:133], v[26:29]
	v_mfma_f32_16x16x32_bf16 v[110:113], v[202:205], v[146:149], v[110:113]
	v_mfma_f32_16x16x32_bf16 v[106:109], v[206:209], v[146:149], v[106:109]
	v_mfma_f32_16x16x32_bf16 v[102:105], v[210:213], v[146:149], v[102:105]
	v_mfma_f32_16x16x32_bf16 v[30:33], v[214:217], v[146:149], v[30:33]
	v_mfma_f32_16x16x32_bf16 v[94:97], v[202:205], v[164:167], v[94:97]
	v_mfma_f32_16x16x32_bf16 v[90:93], v[206:209], v[164:167], v[90:93]
	v_mfma_f32_16x16x32_bf16 v[86:89], v[210:213], v[164:167], v[86:89]
	v_mfma_f32_16x16x32_bf16 v[82:85], v[214:217], v[164:167], v[82:85]
	v_mfma_f32_16x16x32_bf16 v[78:81], v[202:205], v[188:191], v[78:81]
	v_mfma_f32_16x16x32_bf16 v[74:77], v[206:209], v[188:191], v[74:77]
	v_mfma_f32_16x16x32_bf16 v[70:73], v[210:213], v[188:191], v[70:73]
	v_mfma_f32_16x16x32_bf16 v[66:69], v[214:217], v[188:191], v[66:69]
	v_mfma_f32_16x16x32_bf16 v[62:65], v[202:205], v[192:195], v[62:65]
	v_mfma_f32_16x16x32_bf16 v[58:61], v[206:209], v[192:195], v[58:61]
	v_mfma_f32_16x16x32_bf16 v[54:57], v[210:213], v[192:195], v[54:57]
	v_mfma_f32_16x16x32_bf16 v[50:53], v[214:217], v[192:195], v[50:53]
	v_mfma_f32_16x16x32_bf16 v[46:49], v[202:205], v[198:201], v[46:49]
	v_mfma_f32_16x16x32_bf16 v[42:45], v[206:209], v[198:201], v[42:45]
	v_mfma_f32_16x16x32_bf16 v[38:41], v[210:213], v[198:201], v[38:41]
	v_mfma_f32_16x16x32_bf16 v[34:37], v[214:217], v[198:201], v[34:37]
	s_barrier
	s_waitcnt vmcnt(7)
	ds_write_b128 v163, v[168:171]
	s_waitcnt vmcnt(6)
	ds_write_b128 v163, v[172:175] offset:8192
	s_waitcnt vmcnt(5)
	ds_write_b128 v163, v[176:179] offset:16384
	s_waitcnt vmcnt(4)
	ds_write_b128 v163, v[180:183] offset:24576
	v_add3_u32 v176, s7, v0, v187
	ds_read_b128 v[126:129], v176
	ds_read_b128 v[130:133], v176 offset:2048
	ds_read_b128 v[142:145], v176 offset:4096
	ds_read_b128 v[146:149], v176 offset:6144
	ds_read_b128 v[164:167], v176 offset:8192
	ds_read_b128 v[168:171], v176 offset:10240
	ds_read_b128 v[172:175], v176 offset:12288
	ds_read_b128 v[176:179], v176 offset:14336
	v_add3_u32 v0, s20, v0, v186
	ds_read_b128 v[180:183], v0
	ds_read_b128 v[188:191], v0 offset:2048
	ds_read_b128 v[192:195], v0 offset:4096
	ds_read_b128 v[198:201], v0 offset:6144
	s_waitcnt lgkmcnt(3)
	v_mfma_f32_16x16x32_bf16 v[158:161], v[180:183], v[126:129], v[158:161]
	s_waitcnt lgkmcnt(2)
	v_mfma_f32_16x16x32_bf16 v[154:157], v[188:191], v[126:129], v[154:157]
	s_waitcnt lgkmcnt(1)
	v_mfma_f32_16x16x32_bf16 v[150:153], v[192:195], v[126:129], v[150:153]
	s_waitcnt lgkmcnt(0)
	v_mfma_f32_16x16x32_bf16 v[18:21], v[198:201], v[126:129], v[18:21]
	v_mfma_f32_16x16x32_bf16 v[98:101], v[180:183], v[130:133], v[98:101]
	v_mfma_f32_16x16x32_bf16 v[126:129], v[188:191], v[130:133], v[138:141]
	v_mfma_f32_16x16x32_bf16 v[22:25], v[198:201], v[130:133], v[22:25]
	v_mfma_f32_16x16x32_bf16 v[114:117], v[180:183], v[142:145], v[114:117]
	v_mfma_f32_16x16x32_bf16 v[122:125], v[188:191], v[142:145], v[122:125]
	v_mfma_f32_16x16x32_bf16 v[118:121], v[192:195], v[142:145], v[118:121]
	v_mfma_f32_16x16x32_bf16 v[26:29], v[198:201], v[142:145], v[26:29]
	v_mfma_f32_16x16x32_bf16 v[30:33], v[198:201], v[146:149], v[30:33]
	v_mfma_f32_16x16x32_bf16 v[134:137], v[192:195], v[130:133], v[134:137]
	v_mfma_f32_16x16x32_bf16 v[130:133], v[180:183], v[146:149], v[110:113]
	v_mfma_f32_16x16x32_bf16 v[138:141], v[188:191], v[146:149], v[106:109]
	v_mfma_f32_16x16x32_bf16 v[142:145], v[192:195], v[146:149], v[102:105]
	v_mfma_f32_16x16x32_bf16 v[146:149], v[180:183], v[164:167], v[94:97]
	v_mfma_f32_16x16x32_bf16 v[202:205], v[188:191], v[164:167], v[90:93]
	v_mfma_f32_16x16x32_bf16 v[206:209], v[192:195], v[164:167], v[86:89]
	v_mfma_f32_16x16x32_bf16 v[164:167], v[198:201], v[164:167], v[82:85]
	v_mfma_f32_16x16x32_bf16 v[210:213], v[180:183], v[168:171], v[78:81]
	v_mfma_f32_16x16x32_bf16 v[214:217], v[188:191], v[168:171], v[74:77]
	v_mfma_f32_16x16x32_bf16 v[218:221], v[192:195], v[168:171], v[70:73]
	v_mfma_f32_16x16x32_bf16 v[168:171], v[198:201], v[168:171], v[66:69]
	v_mfma_f32_16x16x32_bf16 v[222:225], v[180:183], v[172:175], v[62:65]
	v_mfma_f32_16x16x32_bf16 v[226:229], v[188:191], v[172:175], v[58:61]
	v_mfma_f32_16x16x32_bf16 v[230:233], v[192:195], v[172:175], v[54:57]
	v_mfma_f32_16x16x32_bf16 v[172:175], v[198:201], v[172:175], v[50:53]
	v_mfma_f32_16x16x32_bf16 v[180:183], v[180:183], v[176:179], v[46:49]
	v_mfma_f32_16x16x32_bf16 v[188:191], v[188:191], v[176:179], v[42:45]
	v_mfma_f32_16x16x32_bf16 v[192:195], v[192:195], v[176:179], v[38:41]
	v_mfma_f32_16x16x32_bf16 v[176:179], v[198:201], v[176:179], v[34:37]
	s_waitcnt vmcnt(3)
	ds_write_b128 v163, v[2:5] offset:32768
	s_waitcnt vmcnt(2)
	ds_write_b128 v163, v[6:9] offset:40960
	s_waitcnt vmcnt(1)
; DI int TID8() { int t = threadIdx.x; asm volatile("" : "+v"(t)); return t; }
; DI void gemm8_accum(f32x4 (&acc)[8][4], const bf16_t* a, size_t lda, const bf16_t* b, size_t ldb, int nkb, bf16_t* L,
;                     const bool pre, const bf16_t* an, size_t ldan, const bf16_t* bn, size_t ldbn) {
;     ...
;   g8_compute<0, 1>(acc, L + 32768, wm, wn, lane);
;   __builtin_amdgcn_sched_barrier(0);
;   g8_store1(L + 16384, rb, lrow, lch);
;   __builtin_amdgcn_sched_barrier(0);
;   g8_compute<1, 2>(acc, L + 32768, wm, wn, lane);
; DI void gemm8_epi_resid(f32x4 (&acc)[8][4], int m0, int n0, int ntile8, bf16_t* L, const float* xin, float* out, bf16_t* xb, float* rowpart) {
;   const int tid = TID8(), lane = tid & 63, w = tid >> 6;
;   const int wm = w >> 2, wn = w & 3;
;   float* red = (float*)(L + 32768);
; #pragma unroll
;   for (int i = 0; i < 8; ++i) {
;     const int ml = wm * 128 + i * 16 + (lane & 15);
;     const size_t rowoff = (size_t)(m0 + ml) * DM;
;     float ss = 0.f;
; #pragma unroll
;     for (int j = 0; j < 4; ++j) {
;       const int n = n0 + wn * 64 + j * 16 + (lane >> 4) * 4;
;       const float4 xv = *(const float4*)(xin + rowoff + n);
;       const float o0 = xv.x + acc[i][j][0], o1 = xv.y + acc[i][j][1], o2 = xv.z + acc[i][j][2], o3 = xv.w + acc[i][j][3];
;       *(float4*)(out + rowoff + n) = make_float4(o0, o1, o2, o3);
	ds_write_b128 v163, v[10:13] offset:49152
	s_waitcnt vmcnt(0)
	ds_write_b128 v163, v[14:17] offset:57344
	v_add3_u32 v0, s7, v184, v187
	ds_read_b128 v[2:5], v0
	ds_read_b128 v[6:9], v0 offset:2048
	ds_read_b128 v[10:13], v0 offset:4096
	ds_read_b128 v[14:17], v0 offset:6144
	ds_read_b128 v[34:37], v0 offset:8192
	ds_read_b128 v[198:201], v0 offset:10240
	ds_read_b128 v[234:237], v0 offset:12288
	ds_read_b128 v[238:241], v0 offset:14336
	v_add3_u32 v0, s20, v184, v186
	ds_read_b128 v[184:187], v0
	ds_read_b128 v[242:245], v0 offset:2048
	ds_read_b128 v[246:249], v0 offset:4096
	ds_read_b128 v[38:41], v0 offset:6144
	s_waitcnt lgkmcnt(3)
	v_mfma_f32_16x16x32_bf16 v[158:161], v[184:187], v[2:5], v[158:161]
	s_waitcnt lgkmcnt(2)
	v_mfma_f32_16x16x32_bf16 v[154:157], v[242:245], v[2:5], v[154:157]
	s_waitcnt lgkmcnt(1)
	v_mfma_f32_16x16x32_bf16 v[150:153], v[246:249], v[2:5], v[150:153]
	s_waitcnt lgkmcnt(0)
	v_mfma_f32_16x16x32_bf16 v[2:5], v[38:41], v[2:5], v[18:21]
	v_mfma_f32_16x16x32_bf16 v[110:113], v[184:187], v[6:9], v[98:101]
	v_mfma_f32_16x16x32_bf16 v[106:109], v[242:245], v[6:9], v[126:129]
	v_mfma_f32_16x16x32_bf16 v[102:105], v[246:249], v[6:9], v[134:137]
	v_mfma_f32_16x16x32_bf16 v[98:101], v[38:41], v[6:9], v[22:25]
	v_mfma_f32_16x16x32_bf16 v[94:97], v[184:187], v[10:13], v[114:117]
	v_mfma_f32_16x16x32_bf16 v[90:93], v[242:245], v[10:13], v[122:125]
	v_mfma_f32_16x16x32_bf16 v[86:89], v[246:249], v[10:13], v[118:121]
	v_mfma_f32_16x16x32_bf16 v[82:85], v[38:41], v[10:13], v[26:29]
	v_mfma_f32_16x16x32_bf16 v[78:81], v[184:187], v[14:17], v[130:133]
	v_mfma_f32_16x16x32_bf16 v[74:77], v[242:245], v[14:17], v[138:141]
	v_mfma_f32_16x16x32_bf16 v[70:73], v[246:249], v[14:17], v[142:145]
	v_mfma_f32_16x16x32_bf16 v[66:69], v[38:41], v[14:17], v[30:33]
	v_mfma_f32_16x16x32_bf16 v[62:65], v[184:187], v[34:37], v[146:149]
	v_mfma_f32_16x16x32_bf16 v[58:61], v[242:245], v[34:37], v[202:205]
	v_mfma_f32_16x16x32_bf16 v[54:57], v[246:249], v[34:37], v[206:209]
	v_mfma_f32_16x16x32_bf16 v[50:53], v[38:41], v[34:37], v[164:167]
	v_mfma_f32_16x16x32_bf16 v[46:49], v[184:187], v[198:201], v[210:213]
	v_mfma_f32_16x16x32_bf16 v[42:45], v[242:245], v[198:201], v[214:217]
	v_mfma_f32_16x16x32_bf16 v[124:127], v[246:249], v[198:201], v[218:221]
	v_mfma_f32_16x16x32_bf16 v[34:37], v[38:41], v[198:201], v[168:171]
	v_mfma_f32_16x16x32_bf16 v[30:33], v[184:187], v[234:237], v[222:225]
	v_mfma_f32_16x16x32_bf16 v[26:29], v[242:245], v[234:237], v[226:229]
	v_mfma_f32_16x16x32_bf16 v[22:25], v[246:249], v[234:237], v[230:233]
	v_mfma_f32_16x16x32_bf16 v[18:21], v[38:41], v[234:237], v[172:175]
	v_mfma_f32_16x16x32_bf16 v[14:17], v[184:187], v[238:241], v[180:183]
	v_mfma_f32_16x16x32_bf16 v[10:13], v[242:245], v[238:241], v[188:191]
	v_mfma_f32_16x16x32_bf16 v[6:9], v[246:249], v[238:241], v[192:195]
	v_mfma_f32_16x16x32_bf16 v[38:41], v[38:41], v[238:241], v[176:179]
	v_mov_b32_e32 v118, v196
	s_barrier
	s_movk_i32 s2, 0xff80
	v_ashrrev_i32_e32 v115, 1, v118
	v_and_b32_e32 v116, 15, v118
	v_bfe_u32 v114, v118, 6, 2
	v_and_or_b32 v121, v115, s2, v116
	v_lshrrev_b32_e32 v116, 2, v118
	v_and_b32_e32 v0, 63, v118
	v_lshlrev_b32_e32 v115, 6, v114
	v_and_b32_e32 v116, 12, v116
	v_or3_b32 v138, v116, s13, v115
	v_lshlrev_b32_e32 v115, 2, v0
	v_lshl_add_u32 v146, v114, 10, s7
	v_add_u32_e32 v114, s6, v121
	v_xor_b32_e32 v120, 64, v115
	v_xor_b32_e32 v119, 0x80, v115
	v_ashrrev_i32_e32 v115, 31, v114
	v_readlane_b32 s24, v251, 33
	v_lshlrev_b64 v[116:117], 12, v[114:115]
	v_readlane_b32 s26, v251, 35
	v_readlane_b32 s27, v251, 36
	v_cmp_gt_u32_e32 vcc, 16, v0
	v_lshlrev_b32_e32 v0, 2, v138
	v_lshl_add_u64 v[116:117], s[26:27], 0, v[116:117]
	v_lshl_add_u64 v[132:133], v[116:117], 0, v[0:1]
	v_lshlrev_b64 v[122:123], 11, v[114:115]
	v_lshl_add_u64 v[122:123], s[18:19], 0, v[122:123]
	v_lshlrev_b32_e32 v116, 1, v138
	v_mov_b32_e32 v117, v1
	v_lshl_add_u64 v[122:123], v[122:123], 0, v[116:117]
	v_readlane_b32 s25, v251, 34
	v_lshl_add_u32 v188, v121, 2, v146
	v_mov_b32_e32 v189, v120
	v_mov_b32_e32 v190, v119
	v_and_b32_e32 v240, 63, v118
	v_cmp_gt_u32_e64 s[88:89], 16, v240
	v_and_b32_e32 v243, 15, v118
	v_bfe_u32 v242, v118, 4, 2
	v_and_b32_e32 v240, 8, v243
	v_cmp_eq_u32_e64 s[90:91], 0, v240
	v_lshlrev_b32_e32 v236, 12, v243
	v_lshl_or_b32 v236, v242, 4, v236
	v_lshlrev_b32_e32 v237, 11, v243
	v_lshl_or_b32 v237, v242, 3, v237
	v_sub_co_u32_e32 v238, vcc, v132, v236
	v_subbrev_co_u32_e32 v239, vcc, 0, v133, vcc
	s_nop 0
	v_readfirstlane_b32 s40, v238
	v_readfirstlane_b32 s41, v239
	v_sub_co_u32_e32 v238, vcc, v132, v236
	v_subbrev_co_u32_e32 v239, vcc, 0, v133, vcc
	s_nop 0
	v_readfirstlane_b32 s44, v238
	v_readfirstlane_b32 s45, v239
	v_sub_co_u32_e32 v238, vcc, v122, v237
	v_subbrev_co_u32_e32 v239, vcc, 0, v123, vcc
	s_nop 0
	v_readfirstlane_b32 s48, v238
	v_readfirstlane_b32 s49, v239
	s_add_u32 s42, s40, 0x8000
	s_addc_u32 s43, s41, 0
	s_add_u32 s46, s44, 0x8000
	s_addc_u32 s47, s45, 0
	s_add_u32 s50, s48, 0x4000
	s_addc_u32 s51, s49, 0
	v_and_b32_e32 v238, 7, v243
	v_lshrrev_b32_e32 v239, 3, v243
	v_lshlrev_b32_e32 v244, 12, v238
	v_lshl_or_b32 v244, v239, 6, v244
	v_lshl_or_b32 v244, v242, 4, v244
	v_lshlrev_b32_e32 v245, 11, v238
	v_lshl_or_b32 v245, v239, 5, v245
	v_lshl_or_b32 v245, v242, 3, v245
	global_load_dwordx4 v[192:195], v244, s[40:41]
	global_load_dwordx4 v[198:201], v244, s[40:41] offset:128
	global_load_dwordx4 v[202:205], v244, s[42:43]
	global_load_dwordx4 v[206:209], v244, s[42:43] offset:128
	s_add_u32 s40, s40, 0x10000
	s_addc_u32 s41, s41, 0
	s_add_u32 s42, s42, 0x10000
	s_addc_u32 s43, s43, 0
	global_load_dwordx4 v[216:219], v244, s[40:41]
	global_load_dwordx4 v[220:223], v244, s[40:41] offset:128
	global_load_dwordx4 v[224:227], v244, s[42:43]
	global_load_dwordx4 v[228:231], v244, s[42:43] offset:128
	s_add_u32 s40, s40, 0x10000
	s_addc_u32 s41, s41, 0
	s_add_u32 s42, s42, 0x10000
	s_addc_u32 s43, s43, 0
	s_waitcnt vmcnt(4)
; DI void gemm8_epi_resid(f32x4 (&acc)[8][4], int m0, int n0, int ntile8, bf16_t* L, const float* xin, float* out, bf16_t* xb, float* rowpart) {
;     ...
;   for (int i = 0; i < 8; ++i) {
;     const int ml = wm * 128 + i * 16 + (lane & 15);
;     const size_t rowoff = (size_t)(m0 + ml) * DM;
;     float ss = 0.f;
; #pragma unroll
;     for (int j = 0; j < 4; ++j) {
;       const int n = n0 + wn * 64 + j * 16 + (lane >> 4) * 4;
;       const float4 xv = *(const float4*)(xin + rowoff + n);
;       const float o0 = xv.x + acc[i][j][0], o1 = xv.y + acc[i][j][1], o2 = xv.z + acc[i][j][2], o3 = xv.w + acc[i][j][3];
;       *(float4*)(out + rowoff + n) = make_float4(o0, o1, o2, o3);
;       ss += o0 * o0 + o1 * o1 + o2 * o2 + o3 * o3;
;       uint2 u;
;       u.x = pack2(o0, o1);
;       u.y = pack2(o2, o3);
;       *(uint2*)(xb + rowoff + n) = u;
;     }
;     ss += shx(ss, 16, lane);
;     ss += shx(ss, 32, lane);
;     if ((lane >> 4) == 0) red[wn * 256 + ml] = ss;
	v_mov_b32_dpp v232, v154 row_ror:8 row_mask:0xf bank_mask:0xf
	v_mov_b32_dpp v233, v155 row_ror:8 row_mask:0xf bank_mask:0xf
	v_mov_b32_dpp v234, v156 row_ror:8 row_mask:0xf bank_mask:0xf
	v_mov_b32_dpp v235, v157 row_ror:8 row_mask:0xf bank_mask:0xf
	v_cndmask_b32_e64 v232, v232, v158, s[90:91]
	v_cndmask_b32_e64 v233, v233, v159, s[90:91]
	v_cndmask_b32_e64 v234, v234, v160, s[90:91]
	v_cndmask_b32_e64 v235, v235, v161, s[90:91]
	v_pk_add_f32 v[232:233], v[232:233], v[192:193]
	v_pk_add_f32 v[234:235], v[234:235], v[194:195]
	s_nop 0
	global_store_dwordx4 v244, v[232:235], s[44:45]
	v_cvt_pk_bf16_f32 v240, v232, v233
	v_cvt_pk_bf16_f32 v241, v234, v235
	v_pk_mul_f32 v[236:237], v[232:233], v[232:233]
	v_pk_mul_f32 v[238:239], v[234:235], v[234:235]
	global_store_dwordx2 v245, v[240:241], s[48:49]
	v_add_f32_e32 v242, v236, v237
	v_add_f32_e32 v242, v242, v238
	v_add_f32_e32 v242, v242, v239
	v_mov_b32_dpp v232, v158 row_ror:8 row_mask:0xf bank_mask:0xf
	v_mov_b32_dpp v233, v159 row_ror:8 row_mask:0xf bank_mask:0xf
	v_mov_b32_dpp v234, v160 row_ror:8 row_mask:0xf bank_mask:0xf
	v_mov_b32_dpp v235, v161 row_ror:8 row_mask:0xf bank_mask:0xf
	v_cndmask_b32_e64 v232, v154, v232, s[90:91]
	v_cndmask_b32_e64 v233, v155, v233, s[90:91]
	v_cndmask_b32_e64 v234, v156, v234, s[90:91]
	v_cndmask_b32_e64 v235, v157, v235, s[90:91]
	v_pk_add_f32 v[232:233], v[232:233], v[202:203]
	v_pk_add_f32 v[234:235], v[234:235], v[204:205]
	s_nop 0
	global_store_dwordx4 v244, v[232:235], s[46:47]
	v_cvt_pk_bf16_f32 v240, v232, v233
	v_cvt_pk_bf16_f32 v241, v234, v235
	v_pk_mul_f32 v[236:237], v[232:233], v[232:233]
	v_pk_mul_f32 v[238:239], v[234:235], v[234:235]
	global_store_dwordx2 v245, v[240:241], s[50:51]
	v_add_f32_e32 v191, v236, v237
	v_add_f32_e32 v191, v191, v238
	v_add_f32_e32 v191, v191, v239
	v_mov_b32_dpp v232, v2 row_ror:8 row_mask:0xf bank_mask:0xf
	v_mov_b32_dpp v233, v3 row_ror:8 row_mask:0xf bank_mask:0xf
	v_mov_b32_dpp v234, v4 row_ror:8 row_mask:0xf bank_mask:0xf
	v_mov_b32_dpp v235, v5 row_ror:8 row_mask:0xf bank_mask:0xf
	v_cndmask_b32_e64 v232, v232, v150, s[90:91]
	v_cndmask_b32_e64 v233, v233, v151, s[90:91]
	v_cndmask_b32_e64 v234, v234, v152, s[90:91]
	v_cndmask_b32_e64 v235, v235, v153, s[90:91]
	v_pk_add_f32 v[232:233], v[232:233], v[198:199]
	v_pk_add_f32 v[234:235], v[234:235], v[200:201]
	s_nop 0
	global_store_dwordx4 v244, v[232:235], s[44:45] offset:128
	v_cvt_pk_bf16_f32 v240, v232, v233
	v_cvt_pk_bf16_f32 v241, v234, v235
	v_pk_mul_f32 v[236:237], v[232:233], v[232:233]
	v_pk_mul_f32 v[238:239], v[234:235], v[234:235]
	global_store_dwordx2 v245, v[240:241], s[48:49] offset:64
	v_add_f32_e32 v242, v242, v236
	v_add_f32_e32 v242, v242, v237
	v_add_f32_e32 v242, v242, v238
	v_add_f32_e32 v242, v242, v239
	v_mov_b32_dpp v232, v150 row_ror:8 row_mask:0xf bank_mask:0xf
	v_mov_b32_dpp v233, v151 row_ror:8 row_mask:0xf bank_mask:0xf
	v_mov_b32_dpp v234, v152 row_ror:8 row_mask:0xf bank_mask:0xf
	v_mov_b32_dpp v235, v153 row_ror:8 row_mask:0xf bank_mask:0xf
	v_cndmask_b32_e64 v232, v2, v232, s[90:91]
	v_cndmask_b32_e64 v233, v3, v233, s[90:91]
	v_cndmask_b32_e64 v234, v4, v234, s[90:91]
	v_cndmask_b32_e64 v235, v5, v235, s[90:91]
	v_pk_add_f32 v[232:233], v[232:233], v[206:207]
	v_pk_add_f32 v[234:235], v[234:235], v[208:209]
	s_nop 0
	global_store_dwordx4 v244, v[232:235], s[46:47] offset:128
	v_cvt_pk_bf16_f32 v240, v232, v233
	v_cvt_pk_bf16_f32 v241, v234, v235
	v_pk_mul_f32 v[236:237], v[232:233], v[232:233]
	v_pk_mul_f32 v[238:239], v[234:235], v[234:235]
	global_store_dwordx2 v245, v[240:241], s[50:51] offset:64
	v_add_f32_e32 v191, v191, v236
	v_add_f32_e32 v191, v191, v237
	v_add_f32_e32 v191, v191, v238
	v_add_f32_e32 v191, v191, v239
	s_nop 1
	v_add_f32_dpp v242, v242, v242 row_ror:8 row_mask:0xf bank_mask:0xf
	v_add_f32_dpp v191, v191, v191 row_ror:8 row_mask:0xf bank_mask:0xf
	s_add_u32 s44, s44, 0x10000
	s_addc_u32 s45, s45, 0
	s_add_u32 s46, s46, 0x10000
	s_addc_u32 s47, s47, 0
	s_add_u32 s48, s48, 0x8000
	s_addc_u32 s49, s49, 0
	s_add_u32 s50, s50, 0x8000
	s_addc_u32 s51, s51, 0
	v_cndmask_b32_e64 v242, v191, v242, s[90:91]
	ds_bpermute_b32 v243, v189, v242
	global_load_dwordx4 v[192:195], v244, s[40:41]
	global_load_dwordx4 v[198:201], v244, s[40:41] offset:128
	global_load_dwordx4 v[202:205], v244, s[42:43]
	global_load_dwordx4 v[206:209], v244, s[42:43] offset:128
	s_add_u32 s40, s40, 0x10000
	s_addc_u32 s41, s41, 0
	s_add_u32 s42, s42, 0x10000
	s_addc_u32 s43, s43, 0
	s_waitcnt lgkmcnt(0)
	v_add_f32_e32 v242, v242, v243
	ds_bpermute_b32 v243, v190, v242
	s_waitcnt lgkmcnt(0)
	v_add_f32_e32 v242, v242, v243
	s_and_saveexec_b64 s[2:3], s[88:89]
	ds_write_b32 v188, v242
	s_or_b64 exec, exec, s[2:3]
	s_waitcnt vmcnt(12)
; DI void gemm8_epi_resid(f32x4 (&acc)[8][4], int m0, int n0, int ntile8, bf16_t* L, const float* xin, float* out, bf16_t* xb, float* rowpart) {
;     ...
;   for (int i = 0; i < 8; ++i) {
;     const int ml = wm * 128 + i * 16 + (lane & 15);
;     const size_t rowoff = (size_t)(m0 + ml) * DM;
;     float ss = 0.f;
; #pragma unroll
;     for (int j = 0; j < 4; ++j) {
;       const int n = n0 + wn * 64 + j * 16 + (lane >> 4) * 4;
;       const float4 xv = *(const float4*)(xin + rowoff + n);
;       const float o0 = xv.x + acc[i][j][0], o1 = xv.y + acc[i][j][1], o2 = xv.z + acc[i][j][2], o3 = xv.w + acc[i][j][3];
;       *(float4*)(out + rowoff + n) = make_float4(o0, o1, o2, o3);
;       ss += o0 * o0 + o1 * o1 + o2 * o2 + o3 * o3;
;       uint2 u;
;       u.x = pack2(o0, o1);
;       u.y = pack2(o2, o3);
;       *(uint2*)(xb + rowoff + n) = u;
;     }
;     ss += shx(ss, 16, lane);
;     ss += shx(ss, 32, lane);
;     if ((lane >> 4) == 0) red[wn * 256 + ml] = ss;
	v_mov_b32_dpp v232, v106 row_ror:8 row_mask:0xf bank_mask:0xf
	v_mov_b32_dpp v233, v107 row_ror:8 row_mask:0xf bank_mask:0xf
	v_mov_b32_dpp v234, v108 row_ror:8 row_mask:0xf bank_mask:0xf
	v_mov_b32_dpp v235, v109 row_ror:8 row_mask:0xf bank_mask:0xf
	v_cndmask_b32_e64 v232, v232, v110, s[90:91]
	v_cndmask_b32_e64 v233, v233, v111, s[90:91]
	v_cndmask_b32_e64 v234, v234, v112, s[90:91]
	v_cndmask_b32_e64 v235, v235, v113, s[90:91]
	v_pk_add_f32 v[232:233], v[232:233], v[216:217]
	v_pk_add_f32 v[234:235], v[234:235], v[218:219]
	s_nop 0
	global_store_dwordx4 v244, v[232:235], s[44:45]
	v_cvt_pk_bf16_f32 v240, v232, v233
	v_cvt_pk_bf16_f32 v241, v234, v235
	v_pk_mul_f32 v[236:237], v[232:233], v[232:233]
	v_pk_mul_f32 v[238:239], v[234:235], v[234:235]
	global_store_dwordx2 v245, v[240:241], s[48:49]
	v_add_f32_e32 v242, v236, v237
	v_add_f32_e32 v242, v242, v238
	v_add_f32_e32 v242, v242, v239
	v_mov_b32_dpp v232, v110 row_ror:8 row_mask:0xf bank_mask:0xf
	v_mov_b32_dpp v233, v111 row_ror:8 row_mask:0xf bank_mask:0xf
	v_mov_b32_dpp v234, v112 row_ror:8 row_mask:0xf bank_mask:0xf
	v_mov_b32_dpp v235, v113 row_ror:8 row_mask:0xf bank_mask:0xf
	v_cndmask_b32_e64 v232, v106, v232, s[90:91]
	v_cndmask_b32_e64 v233, v107, v233, s[90:91]
	v_cndmask_b32_e64 v234, v108, v234, s[90:91]
	v_cndmask_b32_e64 v235, v109, v235, s[90:91]
	v_pk_add_f32 v[232:233], v[232:233], v[224:225]
	v_pk_add_f32 v[234:235], v[234:235], v[226:227]
	s_nop 0
	global_store_dwordx4 v244, v[232:235], s[46:47]
	v_cvt_pk_bf16_f32 v240, v232, v233
	v_cvt_pk_bf16_f32 v241, v234, v235
	v_pk_mul_f32 v[236:237], v[232:233], v[232:233]
	v_pk_mul_f32 v[238:239], v[234:235], v[234:235]
	global_store_dwordx2 v245, v[240:241], s[50:51]
	v_add_f32_e32 v191, v236, v237
	v_add_f32_e32 v191, v191, v238
	v_add_f32_e32 v191, v191, v239
	v_mov_b32_dpp v232, v98 row_ror:8 row_mask:0xf bank_mask:0xf
	v_mov_b32_dpp v233, v99 row_ror:8 row_mask:0xf bank_mask:0xf
	v_mov_b32_dpp v234, v100 row_ror:8 row_mask:0xf bank_mask:0xf
	v_mov_b32_dpp v235, v101 row_ror:8 row_mask:0xf bank_mask:0xf
	v_cndmask_b32_e64 v232, v232, v102, s[90:91]
	v_cndmask_b32_e64 v233, v233, v103, s[90:91]
	v_cndmask_b32_e64 v234, v234, v104, s[90:91]
	v_cndmask_b32_e64 v235, v235, v105, s[90:91]
	v_pk_add_f32 v[232:233], v[232:233], v[220:221]
	v_pk_add_f32 v[234:235], v[234:235], v[222:223]
	s_nop 0
	global_store_dwordx4 v244, v[232:235], s[44:45] offset:128
	v_cvt_pk_bf16_f32 v240, v232, v233
	v_cvt_pk_bf16_f32 v241, v234, v235
	v_pk_mul_f32 v[236:237], v[232:233], v[232:233]
	v_pk_mul_f32 v[238:239], v[234:235], v[234:235]
	global_store_dwordx2 v245, v[240:241], s[48:49] offset:64
	v_add_f32_e32 v242, v242, v236
	v_add_f32_e32 v242, v242, v237
	v_add_f32_e32 v242, v242, v238
	v_add_f32_e32 v242, v242, v239
	v_mov_b32_dpp v232, v102 row_ror:8 row_mask:0xf bank_mask:0xf
	v_mov_b32_dpp v233, v103 row_ror:8 row_mask:0xf bank_mask:0xf
	v_mov_b32_dpp v234, v104 row_ror:8 row_mask:0xf bank_mask:0xf
	v_mov_b32_dpp v235, v105 row_ror:8 row_mask:0xf bank_mask:0xf
	v_cndmask_b32_e64 v232, v98, v232, s[90:91]
	v_cndmask_b32_e64 v233, v99, v233, s[90:91]
	v_cndmask_b32_e64 v234, v100, v234, s[90:91]
	v_cndmask_b32_e64 v235, v101, v235, s[90:91]
	v_pk_add_f32 v[232:233], v[232:233], v[228:229]
	v_pk_add_f32 v[234:235], v[234:235], v[230:231]
	s_nop 0
	global_store_dwordx4 v244, v[232:235], s[46:47] offset:128
	v_cvt_pk_bf16_f32 v240, v232, v233
	v_cvt_pk_bf16_f32 v241, v234, v235
	v_pk_mul_f32 v[236:237], v[232:233], v[232:233]
	v_pk_mul_f32 v[238:239], v[234:235], v[234:235]
	global_store_dwordx2 v245, v[240:241], s[50:51] offset:64
	v_add_f32_e32 v191, v191, v236
	v_add_f32_e32 v191, v191, v237
	v_add_f32_e32 v191, v191, v238
	v_add_f32_e32 v191, v191, v239
	s_nop 1
	v_add_f32_dpp v242, v242, v242 row_ror:8 row_mask:0xf bank_mask:0xf
	v_add_f32_dpp v191, v191, v191 row_ror:8 row_mask:0xf bank_mask:0xf
	s_add_u32 s44, s44, 0x10000
	s_addc_u32 s45, s45, 0
	s_add_u32 s46, s46, 0x10000
	s_addc_u32 s47, s47, 0
	s_add_u32 s48, s48, 0x8000
	s_addc_u32 s49, s49, 0
	s_add_u32 s50, s50, 0x8000
	s_addc_u32 s51, s51, 0
	v_cndmask_b32_e64 v242, v191, v242, s[90:91]
	ds_bpermute_b32 v243, v189, v242
	global_load_dwordx4 v[216:219], v244, s[40:41]
	global_load_dwordx4 v[220:223], v244, s[40:41] offset:128
	global_load_dwordx4 v[224:227], v244, s[42:43]
	global_load_dwordx4 v[228:231], v244, s[42:43] offset:128
	s_add_u32 s40, s40, 0x10000
	s_addc_u32 s41, s41, 0
	s_add_u32 s42, s42, 0x10000
	s_addc_u32 s43, s43, 0
	s_waitcnt lgkmcnt(0)
	v_add_f32_e32 v242, v242, v243
	ds_bpermute_b32 v243, v190, v242
	s_waitcnt lgkmcnt(0)
	v_add_f32_e32 v242, v242, v243
	s_and_saveexec_b64 s[2:3], s[88:89]
	ds_write_b32 v188, v242 offset:64
	s_or_b64 exec, exec, s[2:3]
	s_waitcnt vmcnt(12)
; DI void gemm8_epi_resid(f32x4 (&acc)[8][4], int m0, int n0, int ntile8, bf16_t* L, const float* xin, float* out, bf16_t* xb, float* rowpart) {
;     ...
;   for (int i = 0; i < 8; ++i) {
;     const int ml = wm * 128 + i * 16 + (lane & 15);
;     const size_t rowoff = (size_t)(m0 + ml) * DM;
;     float ss = 0.f;
; #pragma unroll
;     for (int j = 0; j < 4; ++j) {
;       const int n = n0 + wn * 64 + j * 16 + (lane >> 4) * 4;
;       const float4 xv = *(const float4*)(xin + rowoff + n);
;       const float o0 = xv.x + acc[i][j][0], o1 = xv.y + acc[i][j][1], o2 = xv.z + acc[i][j][2], o3 = xv.w + acc[i][j][3];
;       *(float4*)(out + rowoff + n) = make_float4(o0, o1, o2, o3);
;       ss += o0 * o0 + o1 * o1 + o2 * o2 + o3 * o3;
;       uint2 u;
;       u.x = pack2(o0, o1);
;       u.y = pack2(o2, o3);
;       *(uint2*)(xb + rowoff + n) = u;
;     }
;     ss += shx(ss, 16, lane);
;     ss += shx(ss, 32, lane);
;     if ((lane >> 4) == 0) red[wn * 256 + ml] = ss;
;   }
	v_mov_b32_dpp v232, v90 row_ror:8 row_mask:0xf bank_mask:0xf
	v_mov_b32_dpp v233, v91 row_ror:8 row_mask:0xf bank_mask:0xf
	v_mov_b32_dpp v234, v92 row_ror:8 row_mask:0xf bank_mask:0xf
	v_mov_b32_dpp v235, v93 row_ror:8 row_mask:0xf bank_mask:0xf
	v_cndmask_b32_e64 v232, v232, v94, s[90:91]
	v_cndmask_b32_e64 v233, v233, v95, s[90:91]
	v_cndmask_b32_e64 v234, v234, v96, s[90:91]
	v_cndmask_b32_e64 v235, v235, v97, s[90:91]
	v_pk_add_f32 v[232:233], v[232:233], v[192:193]
	v_pk_add_f32 v[234:235], v[234:235], v[194:195]
	s_nop 0
	global_store_dwordx4 v244, v[232:235], s[44:45]
	v_cvt_pk_bf16_f32 v240, v232, v233
	v_cvt_pk_bf16_f32 v241, v234, v235
	v_pk_mul_f32 v[236:237], v[232:233], v[232:233]
	v_pk_mul_f32 v[238:239], v[234:235], v[234:235]
	global_store_dwordx2 v245, v[240:241], s[48:49]
	v_add_f32_e32 v242, v236, v237
	v_add_f32_e32 v242, v242, v238
	v_add_f32_e32 v242, v242, v239
	v_mov_b32_dpp v232, v94 row_ror:8 row_mask:0xf bank_mask:0xf
	v_mov_b32_dpp v233, v95 row_ror:8 row_mask:0xf bank_mask:0xf
	v_mov_b32_dpp v234, v96 row_ror:8 row_mask:0xf bank_mask:0xf
	v_mov_b32_dpp v235, v97 row_ror:8 row_mask:0xf bank_mask:0xf
	v_cndmask_b32_e64 v232, v90, v232, s[90:91]
	v_cndmask_b32_e64 v233, v91, v233, s[90:91]
	v_cndmask_b32_e64 v234, v92, v234, s[90:91]
	v_cndmask_b32_e64 v235, v93, v235, s[90:91]
	v_pk_add_f32 v[232:233], v[232:233], v[202:203]
	v_pk_add_f32 v[234:235], v[234:235], v[204:205]
	s_nop 0
	global_store_dwordx4 v244, v[232:235], s[46:47]
	v_cvt_pk_bf16_f32 v240, v232, v233
	v_cvt_pk_bf16_f32 v241, v234, v235
	v_pk_mul_f32 v[236:237], v[232:233], v[232:233]
	v_pk_mul_f32 v[238:239], v[234:235], v[234:235]
	global_store_dwordx2 v245, v[240:241], s[50:51]
	v_add_f32_e32 v191, v236, v237
	v_add_f32_e32 v191, v191, v238
	v_add_f32_e32 v191, v191, v239
	v_mov_b32_dpp v232, v82 row_ror:8 row_mask:0xf bank_mask:0xf
	v_mov_b32_dpp v233, v83 row_ror:8 row_mask:0xf bank_mask:0xf
	v_mov_b32_dpp v234, v84 row_ror:8 row_mask:0xf bank_mask:0xf
	v_mov_b32_dpp v235, v85 row_ror:8 row_mask:0xf bank_mask:0xf
	v_cndmask_b32_e64 v232, v232, v86, s[90:91]
	v_cndmask_b32_e64 v233, v233, v87, s[90:91]
	v_cndmask_b32_e64 v234, v234, v88, s[90:91]
	v_cndmask_b32_e64 v235, v235, v89, s[90:91]
	v_pk_add_f32 v[232:233], v[232:233], v[198:199]
	v_pk_add_f32 v[234:235], v[234:235], v[200:201]
	s_nop 0
	global_store_dwordx4 v244, v[232:235], s[44:45] offset:128
	v_cvt_pk_bf16_f32 v240, v232, v233
	v_cvt_pk_bf16_f32 v241, v234, v235
	v_pk_mul_f32 v[236:237], v[232:233], v[232:233]
	v_pk_mul_f32 v[238:239], v[234:235], v[234:235]
	global_store_dwordx2 v245, v[240:241], s[48:49] offset:64
	v_add_f32_e32 v242, v242, v236
	v_add_f32_e32 v242, v242, v237
	v_add_f32_e32 v242, v242, v238
	v_add_f32_e32 v242, v242, v239
	v_mov_b32_dpp v232, v86 row_ror:8 row_mask:0xf bank_mask:0xf
	v_mov_b32_dpp v233, v87 row_ror:8 row_mask:0xf bank_mask:0xf
	v_mov_b32_dpp v234, v88 row_ror:8 row_mask:0xf bank_mask:0xf
	v_mov_b32_dpp v235, v89 row_ror:8 row_mask:0xf bank_mask:0xf
	v_cndmask_b32_e64 v232, v82, v232, s[90:91]
	v_cndmask_b32_e64 v233, v83, v233, s[90:91]
	v_cndmask_b32_e64 v234, v84, v234, s[90:91]
	v_cndmask_b32_e64 v235, v85, v235, s[90:91]
	v_pk_add_f32 v[232:233], v[232:233], v[206:207]
	v_pk_add_f32 v[234:235], v[234:235], v[208:209]
	s_nop 0
	global_store_dwordx4 v244, v[232:235], s[46:47] offset:128
	v_cvt_pk_bf16_f32 v240, v232, v233
	v_cvt_pk_bf16_f32 v241, v234, v235
	v_pk_mul_f32 v[236:237], v[232:233], v[232:233]
	v_pk_mul_f32 v[238:239], v[234:235], v[234:235]
	global_store_dwordx2 v245, v[240:241], s[50:51] offset:64
	v_add_f32_e32 v191, v191, v236
	v_add_f32_e32 v191, v191, v237
	v_add_f32_e32 v191, v191, v238
	v_add_f32_e32 v191, v191, v239
	s_nop 1
	v_add_f32_dpp v242, v242, v242 row_ror:8 row_mask:0xf bank_mask:0xf
	v_add_f32_dpp v191, v191, v191 row_ror:8 row_mask:0xf bank_mask:0xf
	s_add_u32 s44, s44, 0x10000
	s_addc_u32 s45, s45, 0
	s_add_u32 s46, s46, 0x10000
	s_addc_u32 s47, s47, 0
	s_add_u32 s48, s48, 0x8000
	s_addc_u32 s49, s49, 0
	s_add_u32 s50, s50, 0x8000
	s_addc_u32 s51, s51, 0
	v_cndmask_b32_e64 v242, v191, v242, s[90:91]
	ds_bpermute_b32 v243, v189, v242
	global_load_dwordx4 v[192:195], v244, s[40:41]
	global_load_dwordx4 v[198:201], v244, s[40:41] offset:128
	global_load_dwordx4 v[202:205], v244, s[42:43]
	global_load_dwordx4 v[206:209], v244, s[42:43] offset:128
	s_add_u32 s40, s40, 0x10000
	s_addc_u32 s41, s41, 0
	s_add_u32 s42, s42, 0x10000
	s_addc_u32 s43, s43, 0
	s_waitcnt lgkmcnt(0)
	v_add_f32_e32 v242, v242, v243
	ds_bpermute_b32 v243, v190, v242
	s_waitcnt lgkmcnt(0)
	v_add_f32_e32 v242, v242, v243
	s_and_saveexec_b64 s[2:3], s[88:89]
	ds_write_b32 v188, v242 offset:128
	s_or_b64 exec, exec, s[2:3]
	s_waitcnt vmcnt(12)
; DI void gemm8_epi_resid(f32x4 (&acc)[8][4], int m0, int n0, int ntile8, bf16_t* L, const float* xin, float* out, bf16_t* xb, float* rowpart) {
;     ...
;   for (int i = 0; i < 8; ++i) {
;     const int ml = wm * 128 + i * 16 + (lane & 15);
;     const size_t rowoff = (size_t)(m0 + ml) * DM;
;     float ss = 0.f;
; #pragma unroll
;     for (int j = 0; j < 4; ++j) {
;       const int n = n0 + wn * 64 + j * 16 + (lane >> 4) * 4;
;       const float4 xv = *(const float4*)(xin + rowoff + n);
;       const float o0 = xv.x + acc[i][j][0], o1 = xv.y + acc[i][j][1], o2 = xv.z + acc[i][j][2], o3 = xv.w + acc[i][j][3];
;       *(float4*)(out + rowoff + n) = make_float4(o0, o1, o2, o3);
;       ss += o0 * o0 + o1 * o1 + o2 * o2 + o3 * o3;
;       uint2 u;
;       u.x = pack2(o0, o1);
;       u.y = pack2(o2, o3);
;       *(uint2*)(xb + rowoff + n) = u;
;     }
;     ss += shx(ss, 16, lane);
;     ss += shx(ss, 32, lane);
;     if ((lane >> 4) == 0) red[wn * 256 + ml] = ss;
;   }
	v_mov_b32_dpp v232, v74 row_ror:8 row_mask:0xf bank_mask:0xf
	v_mov_b32_dpp v233, v75 row_ror:8 row_mask:0xf bank_mask:0xf
	v_mov_b32_dpp v234, v76 row_ror:8 row_mask:0xf bank_mask:0xf
	v_mov_b32_dpp v235, v77 row_ror:8 row_mask:0xf bank_mask:0xf
	v_cndmask_b32_e64 v232, v232, v78, s[90:91]
	v_cndmask_b32_e64 v233, v233, v79, s[90:91]
	v_cndmask_b32_e64 v234, v234, v80, s[90:91]
	v_cndmask_b32_e64 v235, v235, v81, s[90:91]
	v_pk_add_f32 v[232:233], v[232:233], v[216:217]
	v_pk_add_f32 v[234:235], v[234:235], v[218:219]
	s_nop 0
	global_store_dwordx4 v244, v[232:235], s[44:45]
	v_cvt_pk_bf16_f32 v240, v232, v233
	v_cvt_pk_bf16_f32 v241, v234, v235
	v_pk_mul_f32 v[236:237], v[232:233], v[232:233]
	v_pk_mul_f32 v[238:239], v[234:235], v[234:235]
	global_store_dwordx2 v245, v[240:241], s[48:49]
	v_add_f32_e32 v242, v236, v237
	v_add_f32_e32 v242, v242, v238
	v_add_f32_e32 v242, v242, v239
	v_mov_b32_dpp v232, v78 row_ror:8 row_mask:0xf bank_mask:0xf
	v_mov_b32_dpp v233, v79 row_ror:8 row_mask:0xf bank_mask:0xf
	v_mov_b32_dpp v234, v80 row_ror:8 row_mask:0xf bank_mask:0xf
	v_mov_b32_dpp v235, v81 row_ror:8 row_mask:0xf bank_mask:0xf
	v_cndmask_b32_e64 v232, v74, v232, s[90:91]
	v_cndmask_b32_e64 v233, v75, v233, s[90:91]
	v_cndmask_b32_e64 v234, v76, v234, s[90:91]
	v_cndmask_b32_e64 v235, v77, v235, s[90:91]
	v_pk_add_f32 v[232:233], v[232:233], v[224:225]
	v_pk_add_f32 v[234:235], v[234:235], v[226:227]
	s_nop 0
	global_store_dwordx4 v244, v[232:235], s[46:47]
	v_cvt_pk_bf16_f32 v240, v232, v233
	v_cvt_pk_bf16_f32 v241, v234, v235
	v_pk_mul_f32 v[236:237], v[232:233], v[232:233]
	v_pk_mul_f32 v[238:239], v[234:235], v[234:235]
	global_store_dwordx2 v245, v[240:241], s[50:51]
	v_add_f32_e32 v191, v236, v237
	v_add_f32_e32 v191, v191, v238
	v_add_f32_e32 v191, v191, v239
	v_mov_b32_dpp v232, v66 row_ror:8 row_mask:0xf bank_mask:0xf
	v_mov_b32_dpp v233, v67 row_ror:8 row_mask:0xf bank_mask:0xf
	v_mov_b32_dpp v234, v68 row_ror:8 row_mask:0xf bank_mask:0xf
	v_mov_b32_dpp v235, v69 row_ror:8 row_mask:0xf bank_mask:0xf
	v_cndmask_b32_e64 v232, v232, v70, s[90:91]
	v_cndmask_b32_e64 v233, v233, v71, s[90:91]
	v_cndmask_b32_e64 v234, v234, v72, s[90:91]
	v_cndmask_b32_e64 v235, v235, v73, s[90:91]
	v_pk_add_f32 v[232:233], v[232:233], v[220:221]
	v_pk_add_f32 v[234:235], v[234:235], v[222:223]
	s_nop 0
	global_store_dwordx4 v244, v[232:235], s[44:45] offset:128
	v_cvt_pk_bf16_f32 v240, v232, v233
	v_cvt_pk_bf16_f32 v241, v234, v235
	v_pk_mul_f32 v[236:237], v[232:233], v[232:233]
	v_pk_mul_f32 v[238:239], v[234:235], v[234:235]
	global_store_dwordx2 v245, v[240:241], s[48:49] offset:64
	v_add_f32_e32 v242, v242, v236
	v_add_f32_e32 v242, v242, v237
	v_add_f32_e32 v242, v242, v238
	v_add_f32_e32 v242, v242, v239
	v_mov_b32_dpp v232, v70 row_ror:8 row_mask:0xf bank_mask:0xf
	v_mov_b32_dpp v233, v71 row_ror:8 row_mask:0xf bank_mask:0xf
	v_mov_b32_dpp v234, v72 row_ror:8 row_mask:0xf bank_mask:0xf
	v_mov_b32_dpp v235, v73 row_ror:8 row_mask:0xf bank_mask:0xf
	v_cndmask_b32_e64 v232, v66, v232, s[90:91]
	v_cndmask_b32_e64 v233, v67, v233, s[90:91]
	v_cndmask_b32_e64 v234, v68, v234, s[90:91]
	v_cndmask_b32_e64 v235, v69, v235, s[90:91]
	v_pk_add_f32 v[232:233], v[232:233], v[228:229]
	v_pk_add_f32 v[234:235], v[234:235], v[230:231]
	s_nop 0
	global_store_dwordx4 v244, v[232:235], s[46:47] offset:128
	v_cvt_pk_bf16_f32 v240, v232, v233
	v_cvt_pk_bf16_f32 v241, v234, v235
	v_pk_mul_f32 v[236:237], v[232:233], v[232:233]
	v_pk_mul_f32 v[238:239], v[234:235], v[234:235]
	global_store_dwordx2 v245, v[240:241], s[50:51] offset:64
	v_add_f32_e32 v191, v191, v236
	v_add_f32_e32 v191, v191, v237
	v_add_f32_e32 v191, v191, v238
	v_add_f32_e32 v191, v191, v239
	s_nop 1
	v_add_f32_dpp v242, v242, v242 row_ror:8 row_mask:0xf bank_mask:0xf
	v_add_f32_dpp v191, v191, v191 row_ror:8 row_mask:0xf bank_mask:0xf
	s_add_u32 s44, s44, 0x10000
	s_addc_u32 s45, s45, 0
	s_add_u32 s46, s46, 0x10000
	s_addc_u32 s47, s47, 0
	s_add_u32 s48, s48, 0x8000
	s_addc_u32 s49, s49, 0
	s_add_u32 s50, s50, 0x8000
	s_addc_u32 s51, s51, 0
	v_cndmask_b32_e64 v242, v191, v242, s[90:91]
	ds_bpermute_b32 v243, v189, v242
	global_load_dwordx4 v[216:219], v244, s[40:41]
	global_load_dwordx4 v[220:223], v244, s[40:41] offset:128
	global_load_dwordx4 v[224:227], v244, s[42:43]
	global_load_dwordx4 v[228:231], v244, s[42:43] offset:128
	s_add_u32 s40, s40, 0x10000
	s_addc_u32 s41, s41, 0
	s_add_u32 s42, s42, 0x10000
	s_addc_u32 s43, s43, 0
	s_waitcnt lgkmcnt(0)
	v_add_f32_e32 v242, v242, v243
	ds_bpermute_b32 v243, v190, v242
	s_waitcnt lgkmcnt(0)
	v_add_f32_e32 v242, v242, v243
	s_and_saveexec_b64 s[2:3], s[88:89]
	ds_write_b32 v188, v242 offset:192
	s_or_b64 exec, exec, s[2:3]
	s_waitcnt vmcnt(12)
; DI void gemm8_epi_resid(f32x4 (&acc)[8][4], int m0, int n0, int ntile8, bf16_t* L, const float* xin, float* out, bf16_t* xb, float* rowpart) {
;     ...
;   for (int i = 0; i < 8; ++i) {
;     const int ml = wm * 128 + i * 16 + (lane & 15);
;     const size_t rowoff = (size_t)(m0 + ml) * DM;
;     float ss = 0.f;
; #pragma unroll
;     for (int j = 0; j < 4; ++j) {
;       const int n = n0 + wn * 64 + j * 16 + (lane >> 4) * 4;
;       const float4 xv = *(const float4*)(xin + rowoff + n);
;       const float o0 = xv.x + acc[i][j][0], o1 = xv.y + acc[i][j][1], o2 = xv.z + acc[i][j][2], o3 = xv.w + acc[i][j][3];
;       *(float4*)(out + rowoff + n) = make_float4(o0, o1, o2, o3);
;       ss += o0 * o0 + o1 * o1 + o2 * o2 + o3 * o3;
;       uint2 u;
;       u.x = pack2(o0, o1);
;       u.y = pack2(o2, o3);
;       *(uint2*)(xb + rowoff + n) = u;
;     }
;     ss += shx(ss, 16, lane);
;     ss += shx(ss, 32, lane);
;     if ((lane >> 4) == 0) red[wn * 256 + ml] = ss;
;   }
	v_mov_b32_dpp v232, v58 row_ror:8 row_mask:0xf bank_mask:0xf
	v_mov_b32_dpp v233, v59 row_ror:8 row_mask:0xf bank_mask:0xf
	v_mov_b32_dpp v234, v60 row_ror:8 row_mask:0xf bank_mask:0xf
	v_mov_b32_dpp v235, v61 row_ror:8 row_mask:0xf bank_mask:0xf
	v_cndmask_b32_e64 v232, v232, v62, s[90:91]
	v_cndmask_b32_e64 v233, v233, v63, s[90:91]
	v_cndmask_b32_e64 v234, v234, v64, s[90:91]
	v_cndmask_b32_e64 v235, v235, v65, s[90:91]
	v_pk_add_f32 v[232:233], v[232:233], v[192:193]
	v_pk_add_f32 v[234:235], v[234:235], v[194:195]
	s_nop 0
	global_store_dwordx4 v244, v[232:235], s[44:45]
	v_cvt_pk_bf16_f32 v240, v232, v233
	v_cvt_pk_bf16_f32 v241, v234, v235
	v_pk_mul_f32 v[236:237], v[232:233], v[232:233]
	v_pk_mul_f32 v[238:239], v[234:235], v[234:235]
	global_store_dwordx2 v245, v[240:241], s[48:49]
	v_add_f32_e32 v242, v236, v237
	v_add_f32_e32 v242, v242, v238
	v_add_f32_e32 v242, v242, v239
	v_mov_b32_dpp v232, v62 row_ror:8 row_mask:0xf bank_mask:0xf
	v_mov_b32_dpp v233, v63 row_ror:8 row_mask:0xf bank_mask:0xf
	v_mov_b32_dpp v234, v64 row_ror:8 row_mask:0xf bank_mask:0xf
	v_mov_b32_dpp v235, v65 row_ror:8 row_mask:0xf bank_mask:0xf
	v_cndmask_b32_e64 v232, v58, v232, s[90:91]
	v_cndmask_b32_e64 v233, v59, v233, s[90:91]
	v_cndmask_b32_e64 v234, v60, v234, s[90:91]
	v_cndmask_b32_e64 v235, v61, v235, s[90:91]
	v_pk_add_f32 v[232:233], v[232:233], v[202:203]
	v_pk_add_f32 v[234:235], v[234:235], v[204:205]
	s_nop 0
	global_store_dwordx4 v244, v[232:235], s[46:47]
	v_cvt_pk_bf16_f32 v240, v232, v233
	v_cvt_pk_bf16_f32 v241, v234, v235
	v_pk_mul_f32 v[236:237], v[232:233], v[232:233]
	v_pk_mul_f32 v[238:239], v[234:235], v[234:235]
	global_store_dwordx2 v245, v[240:241], s[50:51]
	v_add_f32_e32 v191, v236, v237
	v_add_f32_e32 v191, v191, v238
	v_add_f32_e32 v191, v191, v239
	v_mov_b32_dpp v232, v50 row_ror:8 row_mask:0xf bank_mask:0xf
	v_mov_b32_dpp v233, v51 row_ror:8 row_mask:0xf bank_mask:0xf
	v_mov_b32_dpp v234, v52 row_ror:8 row_mask:0xf bank_mask:0xf
	v_mov_b32_dpp v235, v53 row_ror:8 row_mask:0xf bank_mask:0xf
	v_cndmask_b32_e64 v232, v232, v54, s[90:91]
	v_cndmask_b32_e64 v233, v233, v55, s[90:91]
	v_cndmask_b32_e64 v234, v234, v56, s[90:91]
	v_cndmask_b32_e64 v235, v235, v57, s[90:91]
	v_pk_add_f32 v[232:233], v[232:233], v[198:199]
	v_pk_add_f32 v[234:235], v[234:235], v[200:201]
	s_nop 0
	global_store_dwordx4 v244, v[232:235], s[44:45] offset:128
	v_cvt_pk_bf16_f32 v240, v232, v233
	v_cvt_pk_bf16_f32 v241, v234, v235
	v_pk_mul_f32 v[236:237], v[232:233], v[232:233]
	v_pk_mul_f32 v[238:239], v[234:235], v[234:235]
	global_store_dwordx2 v245, v[240:241], s[48:49] offset:64
	v_add_f32_e32 v242, v242, v236
	v_add_f32_e32 v242, v242, v237
	v_add_f32_e32 v242, v242, v238
	v_add_f32_e32 v242, v242, v239
	v_mov_b32_dpp v232, v54 row_ror:8 row_mask:0xf bank_mask:0xf
	v_mov_b32_dpp v233, v55 row_ror:8 row_mask:0xf bank_mask:0xf
	v_mov_b32_dpp v234, v56 row_ror:8 row_mask:0xf bank_mask:0xf
	v_mov_b32_dpp v235, v57 row_ror:8 row_mask:0xf bank_mask:0xf
	v_cndmask_b32_e64 v232, v50, v232, s[90:91]
	v_cndmask_b32_e64 v233, v51, v233, s[90:91]
	v_cndmask_b32_e64 v234, v52, v234, s[90:91]
	v_cndmask_b32_e64 v235, v53, v235, s[90:91]
	v_pk_add_f32 v[232:233], v[232:233], v[206:207]
	v_pk_add_f32 v[234:235], v[234:235], v[208:209]
	s_nop 0
	global_store_dwordx4 v244, v[232:235], s[46:47] offset:128
	v_cvt_pk_bf16_f32 v240, v232, v233
	v_cvt_pk_bf16_f32 v241, v234, v235
	v_pk_mul_f32 v[236:237], v[232:233], v[232:233]
	v_pk_mul_f32 v[238:239], v[234:235], v[234:235]
	global_store_dwordx2 v245, v[240:241], s[50:51] offset:64
	v_add_f32_e32 v191, v191, v236
	v_add_f32_e32 v191, v191, v237
	v_add_f32_e32 v191, v191, v238
	v_add_f32_e32 v191, v191, v239
	s_nop 1
	v_add_f32_dpp v242, v242, v242 row_ror:8 row_mask:0xf bank_mask:0xf
	v_add_f32_dpp v191, v191, v191 row_ror:8 row_mask:0xf bank_mask:0xf
	s_add_u32 s44, s44, 0x10000
	s_addc_u32 s45, s45, 0
	s_add_u32 s46, s46, 0x10000
	s_addc_u32 s47, s47, 0
	s_add_u32 s48, s48, 0x8000
	s_addc_u32 s49, s49, 0
	s_add_u32 s50, s50, 0x8000
	s_addc_u32 s51, s51, 0
	v_cndmask_b32_e64 v242, v191, v242, s[90:91]
	ds_bpermute_b32 v243, v189, v242
	global_load_dwordx4 v[192:195], v244, s[40:41]
	global_load_dwordx4 v[198:201], v244, s[40:41] offset:128
	global_load_dwordx4 v[202:205], v244, s[42:43]
	global_load_dwordx4 v[206:209], v244, s[42:43] offset:128
	s_add_u32 s40, s40, 0x10000
	s_addc_u32 s41, s41, 0
	s_add_u32 s42, s42, 0x10000
	s_addc_u32 s43, s43, 0
	s_waitcnt lgkmcnt(0)
	v_add_f32_e32 v242, v242, v243
	ds_bpermute_b32 v243, v190, v242
	s_waitcnt lgkmcnt(0)
	v_add_f32_e32 v242, v242, v243
	s_and_saveexec_b64 s[2:3], s[88:89]
	ds_write_b32 v188, v242 offset:256
	s_or_b64 exec, exec, s[2:3]
	s_waitcnt vmcnt(12)
; DI void gemm8_epi_resid(f32x4 (&acc)[8][4], int m0, int n0, int ntile8, bf16_t* L, const float* xin, float* out, bf16_t* xb, float* rowpart) {
;     ...
;   for (int i = 0; i < 8; ++i) {
;     const int ml = wm * 128 + i * 16 + (lane & 15);
;     const size_t rowoff = (size_t)(m0 + ml) * DM;
;     float ss = 0.f;
; #pragma unroll
;     for (int j = 0; j < 4; ++j) {
;       const int n = n0 + wn * 64 + j * 16 + (lane >> 4) * 4;
;       const float4 xv = *(const float4*)(xin + rowoff + n);
;       const float o0 = xv.x + acc[i][j][0], o1 = xv.y + acc[i][j][1], o2 = xv.z + acc[i][j][2], o3 = xv.w + acc[i][j][3];
;       *(float4*)(out + rowoff + n) = make_float4(o0, o1, o2, o3);
;       ss += o0 * o0 + o1 * o1 + o2 * o2 + o3 * o3;
;       uint2 u;
;       u.x = pack2(o0, o1);
;       u.y = pack2(o2, o3);
;       *(uint2*)(xb + rowoff + n) = u;
;     }
;     ss += shx(ss, 16, lane);
;     ss += shx(ss, 32, lane);
;     if ((lane >> 4) == 0) red[wn * 256 + ml] = ss;
;   }
	v_mov_b32_dpp v232, v42 row_ror:8 row_mask:0xf bank_mask:0xf
	v_mov_b32_dpp v233, v43 row_ror:8 row_mask:0xf bank_mask:0xf
	v_mov_b32_dpp v234, v44 row_ror:8 row_mask:0xf bank_mask:0xf
	v_mov_b32_dpp v235, v45 row_ror:8 row_mask:0xf bank_mask:0xf
	v_cndmask_b32_e64 v232, v232, v46, s[90:91]
	v_cndmask_b32_e64 v233, v233, v47, s[90:91]
	v_cndmask_b32_e64 v234, v234, v48, s[90:91]
	v_cndmask_b32_e64 v235, v235, v49, s[90:91]
	v_pk_add_f32 v[232:233], v[232:233], v[216:217]
	v_pk_add_f32 v[234:235], v[234:235], v[218:219]
	s_nop 0
	global_store_dwordx4 v244, v[232:235], s[44:45]
	v_cvt_pk_bf16_f32 v240, v232, v233
	v_cvt_pk_bf16_f32 v241, v234, v235
	v_pk_mul_f32 v[236:237], v[232:233], v[232:233]
	v_pk_mul_f32 v[238:239], v[234:235], v[234:235]
	global_store_dwordx2 v245, v[240:241], s[48:49]
	v_add_f32_e32 v242, v236, v237
	v_add_f32_e32 v242, v242, v238
	v_add_f32_e32 v242, v242, v239
	v_mov_b32_dpp v232, v46 row_ror:8 row_mask:0xf bank_mask:0xf
	v_mov_b32_dpp v233, v47 row_ror:8 row_mask:0xf bank_mask:0xf
	v_mov_b32_dpp v234, v48 row_ror:8 row_mask:0xf bank_mask:0xf
	v_mov_b32_dpp v235, v49 row_ror:8 row_mask:0xf bank_mask:0xf
	v_cndmask_b32_e64 v232, v42, v232, s[90:91]
	v_cndmask_b32_e64 v233, v43, v233, s[90:91]
	v_cndmask_b32_e64 v234, v44, v234, s[90:91]
	v_cndmask_b32_e64 v235, v45, v235, s[90:91]
	v_pk_add_f32 v[232:233], v[232:233], v[224:225]
	v_pk_add_f32 v[234:235], v[234:235], v[226:227]
	s_nop 0
	global_store_dwordx4 v244, v[232:235], s[46:47]
	v_cvt_pk_bf16_f32 v240, v232, v233
	v_cvt_pk_bf16_f32 v241, v234, v235
	v_pk_mul_f32 v[236:237], v[232:233], v[232:233]
	v_pk_mul_f32 v[238:239], v[234:235], v[234:235]
	global_store_dwordx2 v245, v[240:241], s[50:51]
	v_add_f32_e32 v191, v236, v237
	v_add_f32_e32 v191, v191, v238
	v_add_f32_e32 v191, v191, v239
	v_mov_b32_dpp v232, v34 row_ror:8 row_mask:0xf bank_mask:0xf
	v_mov_b32_dpp v233, v35 row_ror:8 row_mask:0xf bank_mask:0xf
	v_mov_b32_dpp v234, v36 row_ror:8 row_mask:0xf bank_mask:0xf
	v_mov_b32_dpp v235, v37 row_ror:8 row_mask:0xf bank_mask:0xf
	v_cndmask_b32_e64 v232, v232, v124, s[90:91]
	v_cndmask_b32_e64 v233, v233, v125, s[90:91]
	v_cndmask_b32_e64 v234, v234, v126, s[90:91]
	v_cndmask_b32_e64 v235, v235, v127, s[90:91]
	v_pk_add_f32 v[232:233], v[232:233], v[220:221]
	v_pk_add_f32 v[234:235], v[234:235], v[222:223]
	s_nop 0
	global_store_dwordx4 v244, v[232:235], s[44:45] offset:128
	v_cvt_pk_bf16_f32 v240, v232, v233
	v_cvt_pk_bf16_f32 v241, v234, v235
	v_pk_mul_f32 v[236:237], v[232:233], v[232:233]
	v_pk_mul_f32 v[238:239], v[234:235], v[234:235]
	global_store_dwordx2 v245, v[240:241], s[48:49] offset:64
	v_add_f32_e32 v242, v242, v236
	v_add_f32_e32 v242, v242, v237
	v_add_f32_e32 v242, v242, v238
	v_add_f32_e32 v242, v242, v239
	v_mov_b32_dpp v232, v124 row_ror:8 row_mask:0xf bank_mask:0xf
	v_mov_b32_dpp v233, v125 row_ror:8 row_mask:0xf bank_mask:0xf
	v_mov_b32_dpp v234, v126 row_ror:8 row_mask:0xf bank_mask:0xf
	v_mov_b32_dpp v235, v127 row_ror:8 row_mask:0xf bank_mask:0xf
	v_cndmask_b32_e64 v232, v34, v232, s[90:91]
	v_cndmask_b32_e64 v233, v35, v233, s[90:91]
	v_cndmask_b32_e64 v234, v36, v234, s[90:91]
	v_cndmask_b32_e64 v235, v37, v235, s[90:91]
	v_pk_add_f32 v[232:233], v[232:233], v[228:229]
	v_pk_add_f32 v[234:235], v[234:235], v[230:231]
	s_nop 0
	global_store_dwordx4 v244, v[232:235], s[46:47] offset:128
	v_cvt_pk_bf16_f32 v240, v232, v233
	v_cvt_pk_bf16_f32 v241, v234, v235
	v_pk_mul_f32 v[236:237], v[232:233], v[232:233]
	v_pk_mul_f32 v[238:239], v[234:235], v[234:235]
	global_store_dwordx2 v245, v[240:241], s[50:51] offset:64
	v_add_f32_e32 v191, v191, v236
	v_add_f32_e32 v191, v191, v237
	v_add_f32_e32 v191, v191, v238
	v_add_f32_e32 v191, v191, v239
	s_nop 1
	v_add_f32_dpp v242, v242, v242 row_ror:8 row_mask:0xf bank_mask:0xf
	v_add_f32_dpp v191, v191, v191 row_ror:8 row_mask:0xf bank_mask:0xf
	s_add_u32 s44, s44, 0x10000
	s_addc_u32 s45, s45, 0
	s_add_u32 s46, s46, 0x10000
	s_addc_u32 s47, s47, 0
	s_add_u32 s48, s48, 0x8000
	s_addc_u32 s49, s49, 0
	s_add_u32 s50, s50, 0x8000
	s_addc_u32 s51, s51, 0
	v_cndmask_b32_e64 v242, v191, v242, s[90:91]
	ds_bpermute_b32 v243, v189, v242
	global_load_dwordx4 v[216:219], v244, s[40:41]
	global_load_dwordx4 v[220:223], v244, s[40:41] offset:128
	global_load_dwordx4 v[224:227], v244, s[42:43]
	global_load_dwordx4 v[228:231], v244, s[42:43] offset:128
	s_add_u32 s40, s40, 0x10000
	s_addc_u32 s41, s41, 0
	s_add_u32 s42, s42, 0x10000
	s_addc_u32 s43, s43, 0
	s_waitcnt lgkmcnt(0)
	v_add_f32_e32 v242, v242, v243
	ds_bpermute_b32 v243, v190, v242
	s_waitcnt lgkmcnt(0)
	v_add_f32_e32 v242, v242, v243
	s_and_saveexec_b64 s[2:3], s[88:89]
	ds_write_b32 v188, v242 offset:320
	s_or_b64 exec, exec, s[2:3]
	s_waitcnt vmcnt(12)
; DI void gemm8_epi_resid(f32x4 (&acc)[8][4], int m0, int n0, int ntile8, bf16_t* L, const float* xin, float* out, bf16_t* xb, float* rowpart) {
;     ...
;   for (int i = 0; i < 8; ++i) {
;     const int ml = wm * 128 + i * 16 + (lane & 15);
;     const size_t rowoff = (size_t)(m0 + ml) * DM;
;     float ss = 0.f;
; #pragma unroll
;     for (int j = 0; j < 4; ++j) {
;       const int n = n0 + wn * 64 + j * 16 + (lane >> 4) * 4;
;       const float4 xv = *(const float4*)(xin + rowoff + n);
;       const float o0 = xv.x + acc[i][j][0], o1 = xv.y + acc[i][j][1], o2 = xv.z + acc[i][j][2], o3 = xv.w + acc[i][j][3];
;       *(float4*)(out + rowoff + n) = make_float4(o0, o1, o2, o3);
;       ss += o0 * o0 + o1 * o1 + o2 * o2 + o3 * o3;
;       uint2 u;
;       u.x = pack2(o0, o1);
;       u.y = pack2(o2, o3);
;       *(uint2*)(xb + rowoff + n) = u;
;     }
;     ss += shx(ss, 16, lane);
;     ss += shx(ss, 32, lane);
;     if ((lane >> 4) == 0) red[wn * 256 + ml] = ss;
;   }
	v_mov_b32_dpp v232, v26 row_ror:8 row_mask:0xf bank_mask:0xf
	v_mov_b32_dpp v233, v27 row_ror:8 row_mask:0xf bank_mask:0xf
	v_mov_b32_dpp v234, v28 row_ror:8 row_mask:0xf bank_mask:0xf
	v_mov_b32_dpp v235, v29 row_ror:8 row_mask:0xf bank_mask:0xf
	v_cndmask_b32_e64 v232, v232, v30, s[90:91]
	v_cndmask_b32_e64 v233, v233, v31, s[90:91]
	v_cndmask_b32_e64 v234, v234, v32, s[90:91]
	v_cndmask_b32_e64 v235, v235, v33, s[90:91]
	v_pk_add_f32 v[232:233], v[232:233], v[192:193]
	v_pk_add_f32 v[234:235], v[234:235], v[194:195]
	s_nop 0
	global_store_dwordx4 v244, v[232:235], s[44:45]
	v_cvt_pk_bf16_f32 v240, v232, v233
	v_cvt_pk_bf16_f32 v241, v234, v235
	v_pk_mul_f32 v[236:237], v[232:233], v[232:233]
	v_pk_mul_f32 v[238:239], v[234:235], v[234:235]
	global_store_dwordx2 v245, v[240:241], s[48:49]
	v_add_f32_e32 v242, v236, v237
	v_add_f32_e32 v242, v242, v238
	v_add_f32_e32 v242, v242, v239
	v_mov_b32_dpp v232, v30 row_ror:8 row_mask:0xf bank_mask:0xf
	v_mov_b32_dpp v233, v31 row_ror:8 row_mask:0xf bank_mask:0xf
	v_mov_b32_dpp v234, v32 row_ror:8 row_mask:0xf bank_mask:0xf
	v_mov_b32_dpp v235, v33 row_ror:8 row_mask:0xf bank_mask:0xf
	v_cndmask_b32_e64 v232, v26, v232, s[90:91]
	v_cndmask_b32_e64 v233, v27, v233, s[90:91]
	v_cndmask_b32_e64 v234, v28, v234, s[90:91]
	v_cndmask_b32_e64 v235, v29, v235, s[90:91]
	v_pk_add_f32 v[232:233], v[232:233], v[202:203]
	v_pk_add_f32 v[234:235], v[234:235], v[204:205]
	s_nop 0
	global_store_dwordx4 v244, v[232:235], s[46:47]
	v_cvt_pk_bf16_f32 v240, v232, v233
	v_cvt_pk_bf16_f32 v241, v234, v235
	v_pk_mul_f32 v[236:237], v[232:233], v[232:233]
	v_pk_mul_f32 v[238:239], v[234:235], v[234:235]
	global_store_dwordx2 v245, v[240:241], s[50:51]
	v_add_f32_e32 v191, v236, v237
	v_add_f32_e32 v191, v191, v238
	v_add_f32_e32 v191, v191, v239
	v_mov_b32_dpp v232, v18 row_ror:8 row_mask:0xf bank_mask:0xf
	v_mov_b32_dpp v233, v19 row_ror:8 row_mask:0xf bank_mask:0xf
	v_mov_b32_dpp v234, v20 row_ror:8 row_mask:0xf bank_mask:0xf
	v_mov_b32_dpp v235, v21 row_ror:8 row_mask:0xf bank_mask:0xf
	v_cndmask_b32_e64 v232, v232, v22, s[90:91]
	v_cndmask_b32_e64 v233, v233, v23, s[90:91]
	v_cndmask_b32_e64 v234, v234, v24, s[90:91]
	v_cndmask_b32_e64 v235, v235, v25, s[90:91]
	v_pk_add_f32 v[232:233], v[232:233], v[198:199]
	v_pk_add_f32 v[234:235], v[234:235], v[200:201]
	s_nop 0
	global_store_dwordx4 v244, v[232:235], s[44:45] offset:128
	v_cvt_pk_bf16_f32 v240, v232, v233
	v_cvt_pk_bf16_f32 v241, v234, v235
	v_pk_mul_f32 v[236:237], v[232:233], v[232:233]
	v_pk_mul_f32 v[238:239], v[234:235], v[234:235]
	global_store_dwordx2 v245, v[240:241], s[48:49] offset:64
	v_add_f32_e32 v242, v242, v236
	v_add_f32_e32 v242, v242, v237
	v_add_f32_e32 v242, v242, v238
	v_add_f32_e32 v242, v242, v239
	v_mov_b32_dpp v232, v22 row_ror:8 row_mask:0xf bank_mask:0xf
	v_mov_b32_dpp v233, v23 row_ror:8 row_mask:0xf bank_mask:0xf
	v_mov_b32_dpp v234, v24 row_ror:8 row_mask:0xf bank_mask:0xf
	v_mov_b32_dpp v235, v25 row_ror:8 row_mask:0xf bank_mask:0xf
	v_cndmask_b32_e64 v232, v18, v232, s[90:91]
	v_cndmask_b32_e64 v233, v19, v233, s[90:91]
	v_cndmask_b32_e64 v234, v20, v234, s[90:91]
	v_cndmask_b32_e64 v235, v21, v235, s[90:91]
	v_pk_add_f32 v[232:233], v[232:233], v[206:207]
	v_pk_add_f32 v[234:235], v[234:235], v[208:209]
	s_nop 0
	global_store_dwordx4 v244, v[232:235], s[46:47] offset:128
	v_cvt_pk_bf16_f32 v240, v232, v233
	v_cvt_pk_bf16_f32 v241, v234, v235
	v_pk_mul_f32 v[236:237], v[232:233], v[232:233]
	v_pk_mul_f32 v[238:239], v[234:235], v[234:235]
	global_store_dwordx2 v245, v[240:241], s[50:51] offset:64
	v_add_f32_e32 v191, v191, v236
	v_add_f32_e32 v191, v191, v237
	v_add_f32_e32 v191, v191, v238
	v_add_f32_e32 v191, v191, v239
	s_nop 1
	v_add_f32_dpp v242, v242, v242 row_ror:8 row_mask:0xf bank_mask:0xf
	v_add_f32_dpp v191, v191, v191 row_ror:8 row_mask:0xf bank_mask:0xf
	s_add_u32 s44, s44, 0x10000
	s_addc_u32 s45, s45, 0
	s_add_u32 s46, s46, 0x10000
	s_addc_u32 s47, s47, 0
	s_add_u32 s48, s48, 0x8000
	s_addc_u32 s49, s49, 0
	s_add_u32 s50, s50, 0x8000
	s_addc_u32 s51, s51, 0
	v_cndmask_b32_e64 v242, v191, v242, s[90:91]
	ds_bpermute_b32 v243, v189, v242
	s_waitcnt lgkmcnt(0)
	v_add_f32_e32 v242, v242, v243
	ds_bpermute_b32 v243, v190, v242
	s_waitcnt lgkmcnt(0)
	v_add_f32_e32 v242, v242, v243
	s_and_saveexec_b64 s[2:3], s[88:89]
	ds_write_b32 v188, v242 offset:384
	s_or_b64 exec, exec, s[2:3]
	s_waitcnt vmcnt(8)
; DI void gemm8_epi_resid(f32x4 (&acc)[8][4], int m0, int n0, int ntile8, bf16_t* L, const float* xin, float* out, bf16_t* xb, float* rowpart) {
;     ...
;   for (int i = 0; i < 8; ++i) {
;     const int ml = wm * 128 + i * 16 + (lane & 15);
;     const size_t rowoff = (size_t)(m0 + ml) * DM;
;     float ss = 0.f;
; #pragma unroll
;     for (int j = 0; j < 4; ++j) {
;       const int n = n0 + wn * 64 + j * 16 + (lane >> 4) * 4;
;       const float4 xv = *(const float4*)(xin + rowoff + n);
;       const float o0 = xv.x + acc[i][j][0], o1 = xv.y + acc[i][j][1], o2 = xv.z + acc[i][j][2], o3 = xv.w + acc[i][j][3];
;       *(float4*)(out + rowoff + n) = make_float4(o0, o1, o2, o3);
;       ss += o0 * o0 + o1 * o1 + o2 * o2 + o3 * o3;
;       uint2 u;
;       u.x = pack2(o0, o1);
;       u.y = pack2(o2, o3);
;       *(uint2*)(xb + rowoff + n) = u;
;     }
;     ss += shx(ss, 16, lane);
;     ss += shx(ss, 32, lane);
;     if ((lane >> 4) == 0) red[wn * 256 + ml] = ss;
;   }
	v_mov_b32_dpp v232, v10 row_ror:8 row_mask:0xf bank_mask:0xf
	v_mov_b32_dpp v233, v11 row_ror:8 row_mask:0xf bank_mask:0xf
	v_mov_b32_dpp v234, v12 row_ror:8 row_mask:0xf bank_mask:0xf
	v_mov_b32_dpp v235, v13 row_ror:8 row_mask:0xf bank_mask:0xf
	v_cndmask_b32_e64 v232, v232, v14, s[90:91]
	v_cndmask_b32_e64 v233, v233, v15, s[90:91]
	v_cndmask_b32_e64 v234, v234, v16, s[90:91]
	v_cndmask_b32_e64 v235, v235, v17, s[90:91]
	v_pk_add_f32 v[232:233], v[232:233], v[216:217]
	v_pk_add_f32 v[234:235], v[234:235], v[218:219]
	s_nop 0
	global_store_dwordx4 v244, v[232:235], s[44:45]
	v_cvt_pk_bf16_f32 v240, v232, v233
	v_cvt_pk_bf16_f32 v241, v234, v235
	v_pk_mul_f32 v[236:237], v[232:233], v[232:233]
	v_pk_mul_f32 v[238:239], v[234:235], v[234:235]
	global_store_dwordx2 v245, v[240:241], s[48:49]
	v_add_f32_e32 v242, v236, v237
	v_add_f32_e32 v242, v242, v238
	v_add_f32_e32 v242, v242, v239
	v_mov_b32_dpp v232, v14 row_ror:8 row_mask:0xf bank_mask:0xf
	v_mov_b32_dpp v233, v15 row_ror:8 row_mask:0xf bank_mask:0xf
	v_mov_b32_dpp v234, v16 row_ror:8 row_mask:0xf bank_mask:0xf
	v_mov_b32_dpp v235, v17 row_ror:8 row_mask:0xf bank_mask:0xf
	v_cndmask_b32_e64 v232, v10, v232, s[90:91]
	v_cndmask_b32_e64 v233, v11, v233, s[90:91]
	v_cndmask_b32_e64 v234, v12, v234, s[90:91]
	v_cndmask_b32_e64 v235, v13, v235, s[90:91]
	v_pk_add_f32 v[232:233], v[232:233], v[224:225]
	v_pk_add_f32 v[234:235], v[234:235], v[226:227]
	s_nop 0
	global_store_dwordx4 v244, v[232:235], s[46:47]
	v_cvt_pk_bf16_f32 v240, v232, v233
	v_cvt_pk_bf16_f32 v241, v234, v235
	v_pk_mul_f32 v[236:237], v[232:233], v[232:233]
	v_pk_mul_f32 v[238:239], v[234:235], v[234:235]
	global_store_dwordx2 v245, v[240:241], s[50:51]
	v_add_f32_e32 v191, v236, v237
	v_add_f32_e32 v191, v191, v238
	v_add_f32_e32 v191, v191, v239
	v_mov_b32_dpp v232, v38 row_ror:8 row_mask:0xf bank_mask:0xf
	v_mov_b32_dpp v233, v39 row_ror:8 row_mask:0xf bank_mask:0xf
	v_mov_b32_dpp v234, v40 row_ror:8 row_mask:0xf bank_mask:0xf
	v_mov_b32_dpp v235, v41 row_ror:8 row_mask:0xf bank_mask:0xf
	v_cndmask_b32_e64 v232, v232, v6, s[90:91]
	v_cndmask_b32_e64 v233, v233, v7, s[90:91]
	v_cndmask_b32_e64 v234, v234, v8, s[90:91]
	v_cndmask_b32_e64 v235, v235, v9, s[90:91]
	v_pk_add_f32 v[232:233], v[232:233], v[220:221]
	v_pk_add_f32 v[234:235], v[234:235], v[222:223]
	s_nop 0
	global_store_dwordx4 v244, v[232:235], s[44:45] offset:128
	v_cvt_pk_bf16_f32 v240, v232, v233
	v_cvt_pk_bf16_f32 v241, v234, v235
	v_pk_mul_f32 v[236:237], v[232:233], v[232:233]
	v_pk_mul_f32 v[238:239], v[234:235], v[234:235]
	global_store_dwordx2 v245, v[240:241], s[48:49] offset:64
	v_add_f32_e32 v242, v242, v236
	v_add_f32_e32 v242, v242, v237
	v_add_f32_e32 v242, v242, v238
	v_add_f32_e32 v242, v242, v239
	v_mov_b32_dpp v232, v6 row_ror:8 row_mask:0xf bank_mask:0xf
	v_mov_b32_dpp v233, v7 row_ror:8 row_mask:0xf bank_mask:0xf
	v_mov_b32_dpp v234, v8 row_ror:8 row_mask:0xf bank_mask:0xf
	v_mov_b32_dpp v235, v9 row_ror:8 row_mask:0xf bank_mask:0xf
	v_cndmask_b32_e64 v232, v38, v232, s[90:91]
	v_cndmask_b32_e64 v233, v39, v233, s[90:91]
	v_cndmask_b32_e64 v234, v40, v234, s[90:91]
	v_cndmask_b32_e64 v235, v41, v235, s[90:91]
	v_pk_add_f32 v[232:233], v[232:233], v[228:229]
	v_pk_add_f32 v[234:235], v[234:235], v[230:231]
	s_nop 0
	global_store_dwordx4 v244, v[232:235], s[46:47] offset:128
	v_cvt_pk_bf16_f32 v240, v232, v233
	v_cvt_pk_bf16_f32 v241, v234, v235
	v_pk_mul_f32 v[236:237], v[232:233], v[232:233]
	v_pk_mul_f32 v[238:239], v[234:235], v[234:235]
	global_store_dwordx2 v245, v[240:241], s[50:51] offset:64
	v_add_f32_e32 v191, v191, v236
	v_add_f32_e32 v191, v191, v237
	v_add_f32_e32 v191, v191, v238
	v_add_f32_e32 v191, v191, v239
	s_nop 1
	v_add_f32_dpp v242, v242, v242 row_ror:8 row_mask:0xf bank_mask:0xf
	v_add_f32_dpp v191, v191, v191 row_ror:8 row_mask:0xf bank_mask:0xf
	s_add_u32 s44, s44, 0x10000
	s_addc_u32 s45, s45, 0
	s_add_u32 s46, s46, 0x10000
	s_addc_u32 s47, s47, 0
	s_add_u32 s48, s48, 0x8000
	s_addc_u32 s49, s49, 0
	s_add_u32 s50, s50, 0x8000
	s_addc_u32 s51, s51, 0
	v_cndmask_b32_e64 v242, v191, v242, s[90:91]
	ds_bpermute_b32 v243, v189, v242
	s_waitcnt lgkmcnt(0)
	v_add_f32_e32 v242, v242, v243
	ds_bpermute_b32 v243, v190, v242
	s_waitcnt lgkmcnt(0)
	v_add_f32_e32 v242, v242, v243
	s_and_saveexec_b64 s[2:3], s[88:89]
	ds_write_b32 v188, v242 offset:448
	s_or_b64 exec, exec, s[2:3]
	s_branch .LBB0_936
